# in-proj and out-proj epilogues write through wave-private LDS stage with row-contiguous global stores
# speedup vs baseline: 1.0653x; 1.0335x over previous
.LBB0_273:
	v_and_b32_e32 v176, 0xffffffc0, v183
	v_lshl_add_u32 v176, s9, 8, v176
	s_movk_i32 s0, 0xe80
	v_cmp_gt_i32_e32 vcc, s0, v176
	s_and_saveexec_b64 s[24:25], vcc
	s_cbranch_execz .LBB0_290
	v_subrev_u32_e32 v177, s8, v184
	v_add_u32_e32 v178, s11, v177
	v_ashrrev_i32_e32 v179, 31, v178
	v_lshl_add_u64 v[180:181], v[178:179], 2, s[14:15]
	global_load_dword v218, v[180:181], off
	global_load_dword v220, v[180:181], off offset:128
	global_load_dword v228, v[180:181], off offset:256
	global_load_dword v230, v[180:181], off offset:384
	s_movk_i32 s0, 0x1ff
	v_cmp_lt_i32_e32 vcc, s0, v176
	v_add_u32_e32 v177, 0xfffff980, v176
	s_movk_i32 s0, 0x13f
	v_cmp_lt_u32_e64 s[0:1], s0, v177
	v_and_b32_e32 v177, 0xffffff40, v176
	s_movk_i32 s8, 0x800
	v_cmp_ne_u32_e64 s[8:9], s8, v177
	s_and_b64 s[0:1], s[0:1], s[8:9]
	s_and_b64 s[0:1], vcc, s[0:1]
	v_cmp_gt_u32_e32 vcc, 32, v182
	s_nop 1
	v_cndmask_b32_e64 v179, 8, 0, vcc
	v_lshlrev_b32_e32 v192, 1, v179
	v_ashrrev_i32_e32 v177, 31, v176
	v_lshrrev_b32_e32 v180, 6, v183
	v_mul_u32_u24_e32 v180, 0x1200, v180
	v_mul_u32_u24_e32 v181, 0x90, v184
	v_add3_u32 v187, v180, v181, v179
	v_lshrrev_b32_e32 v181, 3, v182
	v_and_b32_e32 v179, 7, v182
	v_mul_u32_u24_e32 v186, 0x90, v181
	v_lshl_add_u32 v186, v179, 4, v186
	v_add_u32_e32 v186, v180, v186
	v_sub_u32_e32 v180, v178, v184
	v_add_u32_e32 v180, v180, v181
	v_mov_b32_e32 v184, v187
	v_mov_b64_e32 v[182:183], s[16:17]
	s_movk_i32 s8, 0x1d00
	v_mad_i64_i32 v[182:183], s[8:9], v180, s8, v[182:183]
	v_lshl_add_u64 v[182:183], v[176:177], 1, v[182:183]
	v_lshlrev_b32_e32 v180, 4, v179
	v_mov_b32_e32 v181, v193
	v_lshl_add_u64 v[182:183], v[182:183], 0, v[180:181]
	s_mov_b64 s[8:9], 0xe800
	s_and_b64 vcc, exec, s[0:1]
	s_cbranch_vccnz .Lep1_plain
	v_lshlrev_b32_e32 v198, 5, v178
	v_ashrrev_i32_e32 v199, 31, v198
	v_lshl_add_u64 v[198:199], v[198:199], 2, s[18:19]
	v_lshl_add_u64 v[198:199], v[198:199], 0, v[192:193]
	v_add_co_u32_e32 v188, vcc, 0x1000, v198
	s_nop 1
	v_addc_co_u32_e32 v189, vcc, 0, v199, vcc
	v_add_co_u32_e32 v190, vcc, 0x3000, v198
	s_nop 1
	v_addc_co_u32_e32 v191, vcc, 0, v199, vcc
	global_load_dwordx4 v[202:205], v[188:189], off offset:-4096
	global_load_dwordx4 v[206:209], v[188:189], off offset:-4064
	global_load_dwordx4 v[210:213], v[188:189], off offset:-4032
	global_load_dwordx4 v[214:217], v[188:189], off offset:-4000
	global_load_dwordx4 v[234:237], v[188:189], off
	global_load_dwordx4 v[238:241], v[188:189], off offset:32
	global_load_dwordx4 v[242:245], v[188:189], off offset:64
	global_load_dwordx4 v[246:249], v[188:189], off offset:96
	s_waitcnt vmcnt(11)
	v_pk_mul_f32 v[112:113], v[112:113], v[218:219] op_sel_hi:[1,0]
	v_pk_mul_f32 v[96:97], v[96:97], v[218:219] op_sel_hi:[1,0]
	s_waitcnt vmcnt(7)
	v_lshlrev_b32_e32 v198, 16, v202
	v_lshlrev_b32_e32 v199, 16, v203
	v_and_b32_e32 v202, 0xffff0000, v202
	v_and_b32_e32 v203, 0xffff0000, v203
	v_pk_mul_f32 v[200:201], v[96:97], v[202:203]
	v_pk_mul_f32 v[96:97], v[96:97], v[198:199]
	v_pk_fma_f32 v[200:201], v[112:113], v[198:199], v[200:201] neg_lo:[0,0,1] neg_hi:[0,0,1]
	v_pk_fma_f32 v[96:97], v[112:113], v[202:203], v[96:97]
	v_pk_mul_f32 v[114:115], v[114:115], v[218:219] op_sel_hi:[1,0]
	v_pk_mul_f32 v[98:99], v[98:99], v[218:219] op_sel_hi:[1,0]
	v_lshlrev_b32_e32 v198, 16, v204
	v_lshlrev_b32_e32 v199, 16, v205
	v_and_b32_e32 v204, 0xffff0000, v204
	v_and_b32_e32 v205, 0xffff0000, v205
	v_pk_mul_f32 v[176:177], v[98:99], v[204:205]
	v_pk_mul_f32 v[98:99], v[98:99], v[198:199]
	v_pk_fma_f32 v[176:177], v[114:115], v[198:199], v[176:177] neg_lo:[0,0,1] neg_hi:[0,0,1]
	v_pk_fma_f32 v[98:99], v[114:115], v[204:205], v[98:99]
	v_pk_mul_f32 v[116:117], v[116:117], v[218:219] op_sel_hi:[1,0]
	v_pk_mul_f32 v[100:101], v[100:101], v[218:219] op_sel_hi:[1,0]
	s_waitcnt vmcnt(6)
	v_lshlrev_b32_e32 v198, 16, v206
	v_lshlrev_b32_e32 v199, 16, v207
	v_and_b32_e32 v206, 0xffff0000, v206
	v_and_b32_e32 v207, 0xffff0000, v207
	v_pk_mul_f32 v[178:179], v[100:101], v[206:207]
	v_pk_mul_f32 v[100:101], v[100:101], v[198:199]
	v_pk_fma_f32 v[178:179], v[116:117], v[198:199], v[178:179] neg_lo:[0,0,1] neg_hi:[0,0,1]
	v_pk_fma_f32 v[100:101], v[116:117], v[206:207], v[100:101]
	v_pk_mul_f32 v[118:119], v[118:119], v[218:219] op_sel_hi:[1,0]
	v_pk_mul_f32 v[102:103], v[102:103], v[218:219] op_sel_hi:[1,0]
	v_lshlrev_b32_e32 v198, 16, v208
	v_lshlrev_b32_e32 v199, 16, v209
	v_and_b32_e32 v208, 0xffff0000, v208
	v_and_b32_e32 v209, 0xffff0000, v209
	v_pk_mul_f32 v[180:181], v[102:103], v[208:209]
	v_pk_mul_f32 v[102:103], v[102:103], v[198:199]
	v_pk_fma_f32 v[180:181], v[118:119], v[198:199], v[180:181] neg_lo:[0,0,1] neg_hi:[0,0,1]
	v_pk_fma_f32 v[102:103], v[118:119], v[208:209], v[102:103]
	v_cvt_pk_bf16_f32 v112, v200, v201
	v_cvt_pk_bf16_f32 v113, v176, v177
	v_cvt_pk_bf16_f32 v114, v178, v179
	v_cvt_pk_bf16_f32 v115, v180, v181
	v_cvt_pk_bf16_f32 v116, v96, v97
	v_cvt_pk_bf16_f32 v117, v98, v99
	v_cvt_pk_bf16_f32 v118, v100, v101
	v_cvt_pk_bf16_f32 v119, v102, v103
	ds_write_b64 v184, v[112:113]
	ds_write_b64 v184, v[114:115] offset:16
	ds_write_b64 v184, v[116:117] offset:64
	ds_write_b64 v184, v[118:119] offset:80
	v_pk_mul_f32 v[120:121], v[120:121], v[218:219] op_sel_hi:[1,0]
	v_pk_mul_f32 v[104:105], v[104:105], v[218:219] op_sel_hi:[1,0]
	s_waitcnt vmcnt(5)
	v_lshlrev_b32_e32 v198, 16, v210
	v_lshlrev_b32_e32 v199, 16, v211
	v_and_b32_e32 v210, 0xffff0000, v210
	v_and_b32_e32 v211, 0xffff0000, v211
	v_pk_mul_f32 v[200:201], v[104:105], v[210:211]
	v_pk_mul_f32 v[104:105], v[104:105], v[198:199]
	v_pk_fma_f32 v[200:201], v[120:121], v[198:199], v[200:201] neg_lo:[0,0,1] neg_hi:[0,0,1]
	v_pk_fma_f32 v[104:105], v[120:121], v[210:211], v[104:105]
	v_pk_mul_f32 v[122:123], v[122:123], v[218:219] op_sel_hi:[1,0]
	v_pk_mul_f32 v[106:107], v[106:107], v[218:219] op_sel_hi:[1,0]
	v_lshlrev_b32_e32 v198, 16, v212
	v_lshlrev_b32_e32 v199, 16, v213
	v_and_b32_e32 v212, 0xffff0000, v212
	v_and_b32_e32 v213, 0xffff0000, v213
	v_pk_mul_f32 v[176:177], v[106:107], v[212:213]
	v_pk_mul_f32 v[106:107], v[106:107], v[198:199]
	v_pk_fma_f32 v[176:177], v[122:123], v[198:199], v[176:177] neg_lo:[0,0,1] neg_hi:[0,0,1]
	v_pk_fma_f32 v[106:107], v[122:123], v[212:213], v[106:107]
	v_pk_mul_f32 v[124:125], v[124:125], v[218:219] op_sel_hi:[1,0]
	v_pk_mul_f32 v[108:109], v[108:109], v[218:219] op_sel_hi:[1,0]
	s_waitcnt vmcnt(4)
	v_lshlrev_b32_e32 v198, 16, v214
	v_lshlrev_b32_e32 v199, 16, v215
	v_and_b32_e32 v214, 0xffff0000, v214
	v_and_b32_e32 v215, 0xffff0000, v215
	v_pk_mul_f32 v[178:179], v[108:109], v[214:215]
	v_pk_mul_f32 v[108:109], v[108:109], v[198:199]
	v_pk_fma_f32 v[178:179], v[124:125], v[198:199], v[178:179] neg_lo:[0,0,1] neg_hi:[0,0,1]
	v_pk_fma_f32 v[108:109], v[124:125], v[214:215], v[108:109]
	v_pk_mul_f32 v[126:127], v[126:127], v[218:219] op_sel_hi:[1,0]
	v_pk_mul_f32 v[110:111], v[110:111], v[218:219] op_sel_hi:[1,0]
	v_lshlrev_b32_e32 v198, 16, v216
	v_lshlrev_b32_e32 v199, 16, v217
	v_and_b32_e32 v216, 0xffff0000, v216
	v_and_b32_e32 v217, 0xffff0000, v217
	v_pk_mul_f32 v[180:181], v[110:111], v[216:217]
	v_pk_mul_f32 v[110:111], v[110:111], v[198:199]
	v_pk_fma_f32 v[180:181], v[126:127], v[198:199], v[180:181] neg_lo:[0,0,1] neg_hi:[0,0,1]
	v_pk_fma_f32 v[110:111], v[126:127], v[216:217], v[110:111]
	global_load_dwordx4 v[202:205], v[190:191], off offset:-4096
	global_load_dwordx4 v[206:209], v[190:191], off offset:-4064
	global_load_dwordx4 v[210:213], v[190:191], off offset:-4032
	global_load_dwordx4 v[214:217], v[190:191], off offset:-4000
	v_cvt_pk_bf16_f32 v120, v200, v201
	v_cvt_pk_bf16_f32 v121, v176, v177
	v_cvt_pk_bf16_f32 v122, v178, v179
	v_cvt_pk_bf16_f32 v123, v180, v181
	v_cvt_pk_bf16_f32 v124, v104, v105
	v_cvt_pk_bf16_f32 v125, v106, v107
	v_cvt_pk_bf16_f32 v126, v108, v109
	v_cvt_pk_bf16_f32 v127, v110, v111
	ds_write_b64 v184, v[120:121] offset:32
	ds_write_b64 v184, v[122:123] offset:48
	ds_write_b64 v184, v[124:125] offset:96
	ds_write_b64 v184, v[126:127] offset:112
	ds_read_b128 v[96:99], v186
	ds_read_b128 v[100:103], v186 offset:1152
	ds_read_b128 v[104:107], v186 offset:2304
	ds_read_b128 v[108:111], v186 offset:3456
	s_waitcnt lgkmcnt(3)
	global_store_dwordx4 v[182:183], v[96:99], off
	v_lshl_add_u64 v[182:183], v[182:183], 0, s[8:9]
	s_waitcnt lgkmcnt(2)
	global_store_dwordx4 v[182:183], v[100:103], off
	v_lshl_add_u64 v[182:183], v[182:183], 0, s[8:9]
	s_waitcnt lgkmcnt(1)
	global_store_dwordx4 v[182:183], v[104:107], off
	v_lshl_add_u64 v[182:183], v[182:183], 0, s[8:9]
	s_waitcnt lgkmcnt(0)
	global_store_dwordx4 v[182:183], v[108:111], off
	v_lshl_add_u64 v[182:183], v[182:183], 0, s[8:9]
	v_pk_mul_f32 v[80:81], v[80:81], v[220:221] op_sel_hi:[1,0]
	v_pk_mul_f32 v[64:65], v[64:65], v[220:221] op_sel_hi:[1,0]
	s_waitcnt vmcnt(11)
	v_lshlrev_b32_e32 v198, 16, v234
	v_lshlrev_b32_e32 v199, 16, v235
	v_and_b32_e32 v234, 0xffff0000, v234
	v_and_b32_e32 v235, 0xffff0000, v235
	v_pk_mul_f32 v[200:201], v[64:65], v[234:235]
	v_pk_mul_f32 v[64:65], v[64:65], v[198:199]
	v_pk_fma_f32 v[200:201], v[80:81], v[198:199], v[200:201] neg_lo:[0,0,1] neg_hi:[0,0,1]
	v_pk_fma_f32 v[64:65], v[80:81], v[234:235], v[64:65]
	v_pk_mul_f32 v[82:83], v[82:83], v[220:221] op_sel_hi:[1,0]
	v_pk_mul_f32 v[66:67], v[66:67], v[220:221] op_sel_hi:[1,0]
	v_lshlrev_b32_e32 v198, 16, v236
	v_lshlrev_b32_e32 v199, 16, v237
	v_and_b32_e32 v236, 0xffff0000, v236
	v_and_b32_e32 v237, 0xffff0000, v237
	v_pk_mul_f32 v[176:177], v[66:67], v[236:237]
	v_pk_mul_f32 v[66:67], v[66:67], v[198:199]
	v_pk_fma_f32 v[176:177], v[82:83], v[198:199], v[176:177] neg_lo:[0,0,1] neg_hi:[0,0,1]
	v_pk_fma_f32 v[66:67], v[82:83], v[236:237], v[66:67]
	v_pk_mul_f32 v[84:85], v[84:85], v[220:221] op_sel_hi:[1,0]
	v_pk_mul_f32 v[68:69], v[68:69], v[220:221] op_sel_hi:[1,0]
	s_waitcnt vmcnt(10)
	v_lshlrev_b32_e32 v198, 16, v238
	v_lshlrev_b32_e32 v199, 16, v239
	v_and_b32_e32 v238, 0xffff0000, v238
	v_and_b32_e32 v239, 0xffff0000, v239
	v_pk_mul_f32 v[178:179], v[68:69], v[238:239]
	v_pk_mul_f32 v[68:69], v[68:69], v[198:199]
	v_pk_fma_f32 v[178:179], v[84:85], v[198:199], v[178:179] neg_lo:[0,0,1] neg_hi:[0,0,1]
	v_pk_fma_f32 v[68:69], v[84:85], v[238:239], v[68:69]
	v_pk_mul_f32 v[86:87], v[86:87], v[220:221] op_sel_hi:[1,0]
	v_pk_mul_f32 v[70:71], v[70:71], v[220:221] op_sel_hi:[1,0]
	v_lshlrev_b32_e32 v198, 16, v240
	v_lshlrev_b32_e32 v199, 16, v241
	v_and_b32_e32 v240, 0xffff0000, v240
	v_and_b32_e32 v241, 0xffff0000, v241
	v_pk_mul_f32 v[180:181], v[70:71], v[240:241]
	v_pk_mul_f32 v[70:71], v[70:71], v[198:199]
	v_pk_fma_f32 v[180:181], v[86:87], v[198:199], v[180:181] neg_lo:[0,0,1] neg_hi:[0,0,1]
	v_pk_fma_f32 v[70:71], v[86:87], v[240:241], v[70:71]
	v_cvt_pk_bf16_f32 v80, v200, v201
	v_cvt_pk_bf16_f32 v81, v176, v177
	v_cvt_pk_bf16_f32 v82, v178, v179
	v_cvt_pk_bf16_f32 v83, v180, v181
	v_cvt_pk_bf16_f32 v84, v64, v65
	v_cvt_pk_bf16_f32 v85, v66, v67
	v_cvt_pk_bf16_f32 v86, v68, v69
	v_cvt_pk_bf16_f32 v87, v70, v71
	ds_write_b64 v184, v[80:81]
	ds_write_b64 v184, v[82:83] offset:16
	ds_write_b64 v184, v[84:85] offset:64
	ds_write_b64 v184, v[86:87] offset:80
	v_pk_mul_f32 v[88:89], v[88:89], v[220:221] op_sel_hi:[1,0]
	v_pk_mul_f32 v[72:73], v[72:73], v[220:221] op_sel_hi:[1,0]
	s_waitcnt vmcnt(9)
	v_lshlrev_b32_e32 v198, 16, v242
	v_lshlrev_b32_e32 v199, 16, v243
	v_and_b32_e32 v242, 0xffff0000, v242
	v_and_b32_e32 v243, 0xffff0000, v243
	v_pk_mul_f32 v[200:201], v[72:73], v[242:243]
	v_pk_mul_f32 v[72:73], v[72:73], v[198:199]
	v_pk_fma_f32 v[200:201], v[88:89], v[198:199], v[200:201] neg_lo:[0,0,1] neg_hi:[0,0,1]
	v_pk_fma_f32 v[72:73], v[88:89], v[242:243], v[72:73]
	v_pk_mul_f32 v[90:91], v[90:91], v[220:221] op_sel_hi:[1,0]
	v_pk_mul_f32 v[74:75], v[74:75], v[220:221] op_sel_hi:[1,0]
	v_lshlrev_b32_e32 v198, 16, v244
	v_lshlrev_b32_e32 v199, 16, v245
	v_and_b32_e32 v244, 0xffff0000, v244
	v_and_b32_e32 v245, 0xffff0000, v245
	v_pk_mul_f32 v[176:177], v[74:75], v[244:245]
	v_pk_mul_f32 v[74:75], v[74:75], v[198:199]
	v_pk_fma_f32 v[176:177], v[90:91], v[198:199], v[176:177] neg_lo:[0,0,1] neg_hi:[0,0,1]
	v_pk_fma_f32 v[74:75], v[90:91], v[244:245], v[74:75]
	v_pk_mul_f32 v[92:93], v[92:93], v[220:221] op_sel_hi:[1,0]
	v_pk_mul_f32 v[76:77], v[76:77], v[220:221] op_sel_hi:[1,0]
	s_waitcnt vmcnt(8)
	v_lshlrev_b32_e32 v198, 16, v246
	v_lshlrev_b32_e32 v199, 16, v247
	v_and_b32_e32 v246, 0xffff0000, v246
	v_and_b32_e32 v247, 0xffff0000, v247
	v_pk_mul_f32 v[178:179], v[76:77], v[246:247]
	v_pk_mul_f32 v[76:77], v[76:77], v[198:199]
	v_pk_fma_f32 v[178:179], v[92:93], v[198:199], v[178:179] neg_lo:[0,0,1] neg_hi:[0,0,1]
	v_pk_fma_f32 v[76:77], v[92:93], v[246:247], v[76:77]
	v_pk_mul_f32 v[94:95], v[94:95], v[220:221] op_sel_hi:[1,0]
	v_pk_mul_f32 v[78:79], v[78:79], v[220:221] op_sel_hi:[1,0]
	v_lshlrev_b32_e32 v198, 16, v248
	v_lshlrev_b32_e32 v199, 16, v249
	v_and_b32_e32 v248, 0xffff0000, v248
	v_and_b32_e32 v249, 0xffff0000, v249
	v_pk_mul_f32 v[180:181], v[78:79], v[248:249]
	v_pk_mul_f32 v[78:79], v[78:79], v[198:199]
	v_pk_fma_f32 v[180:181], v[94:95], v[198:199], v[180:181] neg_lo:[0,0,1] neg_hi:[0,0,1]
	v_pk_fma_f32 v[78:79], v[94:95], v[248:249], v[78:79]
	global_load_dwordx4 v[234:237], v[190:191], off
	global_load_dwordx4 v[238:241], v[190:191], off offset:32
	global_load_dwordx4 v[242:245], v[190:191], off offset:64
	global_load_dwordx4 v[246:249], v[190:191], off offset:96
	v_cvt_pk_bf16_f32 v88, v200, v201
	v_cvt_pk_bf16_f32 v89, v176, v177
	v_cvt_pk_bf16_f32 v90, v178, v179
	v_cvt_pk_bf16_f32 v91, v180, v181
	v_cvt_pk_bf16_f32 v92, v72, v73
	v_cvt_pk_bf16_f32 v93, v74, v75
	v_cvt_pk_bf16_f32 v94, v76, v77
	v_cvt_pk_bf16_f32 v95, v78, v79
	ds_write_b64 v184, v[88:89] offset:32
	ds_write_b64 v184, v[90:91] offset:48
	ds_write_b64 v184, v[92:93] offset:96
	ds_write_b64 v184, v[94:95] offset:112
	ds_read_b128 v[64:67], v186
	ds_read_b128 v[68:71], v186 offset:1152
	ds_read_b128 v[72:75], v186 offset:2304
	ds_read_b128 v[76:79], v186 offset:3456
	s_waitcnt lgkmcnt(3)
	global_store_dwordx4 v[182:183], v[64:67], off
	v_lshl_add_u64 v[182:183], v[182:183], 0, s[8:9]
	s_waitcnt lgkmcnt(2)
	global_store_dwordx4 v[182:183], v[68:71], off
	v_lshl_add_u64 v[182:183], v[182:183], 0, s[8:9]
	s_waitcnt lgkmcnt(1)
	global_store_dwordx4 v[182:183], v[72:75], off
	v_lshl_add_u64 v[182:183], v[182:183], 0, s[8:9]
	s_waitcnt lgkmcnt(0)
	global_store_dwordx4 v[182:183], v[76:79], off
	v_lshl_add_u64 v[182:183], v[182:183], 0, s[8:9]
	v_pk_mul_f32 v[48:49], v[48:49], v[228:229] op_sel_hi:[1,0]
	v_pk_mul_f32 v[32:33], v[32:33], v[228:229] op_sel_hi:[1,0]
	s_waitcnt vmcnt(15)
	v_lshlrev_b32_e32 v198, 16, v202
	v_lshlrev_b32_e32 v199, 16, v203
	v_and_b32_e32 v202, 0xffff0000, v202
	v_and_b32_e32 v203, 0xffff0000, v203
	v_pk_mul_f32 v[200:201], v[32:33], v[202:203]
	v_pk_mul_f32 v[32:33], v[32:33], v[198:199]
	v_pk_fma_f32 v[200:201], v[48:49], v[198:199], v[200:201] neg_lo:[0,0,1] neg_hi:[0,0,1]
	v_pk_fma_f32 v[32:33], v[48:49], v[202:203], v[32:33]
	v_pk_mul_f32 v[50:51], v[50:51], v[228:229] op_sel_hi:[1,0]
	v_pk_mul_f32 v[34:35], v[34:35], v[228:229] op_sel_hi:[1,0]
	v_lshlrev_b32_e32 v198, 16, v204
	v_lshlrev_b32_e32 v199, 16, v205
	v_and_b32_e32 v204, 0xffff0000, v204
	v_and_b32_e32 v205, 0xffff0000, v205
	v_pk_mul_f32 v[176:177], v[34:35], v[204:205]
	v_pk_mul_f32 v[34:35], v[34:35], v[198:199]
	v_pk_fma_f32 v[176:177], v[50:51], v[198:199], v[176:177] neg_lo:[0,0,1] neg_hi:[0,0,1]
	v_pk_fma_f32 v[34:35], v[50:51], v[204:205], v[34:35]
	v_pk_mul_f32 v[52:53], v[52:53], v[228:229] op_sel_hi:[1,0]
	v_pk_mul_f32 v[36:37], v[36:37], v[228:229] op_sel_hi:[1,0]
	s_waitcnt vmcnt(14)
	v_lshlrev_b32_e32 v198, 16, v206
	v_lshlrev_b32_e32 v199, 16, v207
	v_and_b32_e32 v206, 0xffff0000, v206
	v_and_b32_e32 v207, 0xffff0000, v207
	v_pk_mul_f32 v[178:179], v[36:37], v[206:207]
	v_pk_mul_f32 v[36:37], v[36:37], v[198:199]
	v_pk_fma_f32 v[178:179], v[52:53], v[198:199], v[178:179] neg_lo:[0,0,1] neg_hi:[0,0,1]
	v_pk_fma_f32 v[36:37], v[52:53], v[206:207], v[36:37]
	v_pk_mul_f32 v[54:55], v[54:55], v[228:229] op_sel_hi:[1,0]
	v_pk_mul_f32 v[38:39], v[38:39], v[228:229] op_sel_hi:[1,0]
	v_lshlrev_b32_e32 v198, 16, v208
	v_lshlrev_b32_e32 v199, 16, v209
	v_and_b32_e32 v208, 0xffff0000, v208
	v_and_b32_e32 v209, 0xffff0000, v209
	v_pk_mul_f32 v[180:181], v[38:39], v[208:209]
	v_pk_mul_f32 v[38:39], v[38:39], v[198:199]
	v_pk_fma_f32 v[180:181], v[54:55], v[198:199], v[180:181] neg_lo:[0,0,1] neg_hi:[0,0,1]
	v_pk_fma_f32 v[38:39], v[54:55], v[208:209], v[38:39]
	v_cvt_pk_bf16_f32 v48, v200, v201
	v_cvt_pk_bf16_f32 v49, v176, v177
	v_cvt_pk_bf16_f32 v50, v178, v179
	v_cvt_pk_bf16_f32 v51, v180, v181
	v_cvt_pk_bf16_f32 v52, v32, v33
	v_cvt_pk_bf16_f32 v53, v34, v35
	v_cvt_pk_bf16_f32 v54, v36, v37
	v_cvt_pk_bf16_f32 v55, v38, v39
	ds_write_b64 v184, v[48:49]
	ds_write_b64 v184, v[50:51] offset:16
	ds_write_b64 v184, v[52:53] offset:64
	ds_write_b64 v184, v[54:55] offset:80
	v_pk_mul_f32 v[56:57], v[56:57], v[228:229] op_sel_hi:[1,0]
	v_pk_mul_f32 v[40:41], v[40:41], v[228:229] op_sel_hi:[1,0]
	s_waitcnt vmcnt(13)
	v_lshlrev_b32_e32 v198, 16, v210
	v_lshlrev_b32_e32 v199, 16, v211
	v_and_b32_e32 v210, 0xffff0000, v210
	v_and_b32_e32 v211, 0xffff0000, v211
	v_pk_mul_f32 v[200:201], v[40:41], v[210:211]
	v_pk_mul_f32 v[40:41], v[40:41], v[198:199]
	v_pk_fma_f32 v[200:201], v[56:57], v[198:199], v[200:201] neg_lo:[0,0,1] neg_hi:[0,0,1]
	v_pk_fma_f32 v[40:41], v[56:57], v[210:211], v[40:41]
	v_pk_mul_f32 v[58:59], v[58:59], v[228:229] op_sel_hi:[1,0]
	v_pk_mul_f32 v[42:43], v[42:43], v[228:229] op_sel_hi:[1,0]
	v_lshlrev_b32_e32 v198, 16, v212
	v_lshlrev_b32_e32 v199, 16, v213
	v_and_b32_e32 v212, 0xffff0000, v212
	v_and_b32_e32 v213, 0xffff0000, v213
	v_pk_mul_f32 v[176:177], v[42:43], v[212:213]
	v_pk_mul_f32 v[42:43], v[42:43], v[198:199]
	v_pk_fma_f32 v[176:177], v[58:59], v[198:199], v[176:177] neg_lo:[0,0,1] neg_hi:[0,0,1]
	v_pk_fma_f32 v[42:43], v[58:59], v[212:213], v[42:43]
	v_pk_mul_f32 v[60:61], v[60:61], v[228:229] op_sel_hi:[1,0]
	v_pk_mul_f32 v[44:45], v[44:45], v[228:229] op_sel_hi:[1,0]
	s_waitcnt vmcnt(12)
	v_lshlrev_b32_e32 v198, 16, v214
	v_lshlrev_b32_e32 v199, 16, v215
	v_and_b32_e32 v214, 0xffff0000, v214
	v_and_b32_e32 v215, 0xffff0000, v215
	v_pk_mul_f32 v[178:179], v[44:45], v[214:215]
	v_pk_mul_f32 v[44:45], v[44:45], v[198:199]
	v_pk_fma_f32 v[178:179], v[60:61], v[198:199], v[178:179] neg_lo:[0,0,1] neg_hi:[0,0,1]
	v_pk_fma_f32 v[44:45], v[60:61], v[214:215], v[44:45]
	v_pk_mul_f32 v[62:63], v[62:63], v[228:229] op_sel_hi:[1,0]
	v_pk_mul_f32 v[46:47], v[46:47], v[228:229] op_sel_hi:[1,0]
	v_lshlrev_b32_e32 v198, 16, v216
	v_lshlrev_b32_e32 v199, 16, v217
	v_and_b32_e32 v216, 0xffff0000, v216
	v_and_b32_e32 v217, 0xffff0000, v217
	v_pk_mul_f32 v[180:181], v[46:47], v[216:217]
	v_pk_mul_f32 v[46:47], v[46:47], v[198:199]
	v_pk_fma_f32 v[180:181], v[62:63], v[198:199], v[180:181] neg_lo:[0,0,1] neg_hi:[0,0,1]
	v_pk_fma_f32 v[46:47], v[62:63], v[216:217], v[46:47]
	v_cvt_pk_bf16_f32 v56, v200, v201
	v_cvt_pk_bf16_f32 v57, v176, v177
	v_cvt_pk_bf16_f32 v58, v178, v179
	v_cvt_pk_bf16_f32 v59, v180, v181
	v_cvt_pk_bf16_f32 v60, v40, v41
	v_cvt_pk_bf16_f32 v61, v42, v43
	v_cvt_pk_bf16_f32 v62, v44, v45
	v_cvt_pk_bf16_f32 v63, v46, v47
	ds_write_b64 v184, v[56:57] offset:32
	ds_write_b64 v184, v[58:59] offset:48
	ds_write_b64 v184, v[60:61] offset:96
	ds_write_b64 v184, v[62:63] offset:112
	ds_read_b128 v[32:35], v186
	ds_read_b128 v[36:39], v186 offset:1152
	ds_read_b128 v[40:43], v186 offset:2304
	ds_read_b128 v[44:47], v186 offset:3456
	s_waitcnt lgkmcnt(3)
	global_store_dwordx4 v[182:183], v[32:35], off
	v_lshl_add_u64 v[182:183], v[182:183], 0, s[8:9]
	s_waitcnt lgkmcnt(2)
	global_store_dwordx4 v[182:183], v[36:39], off
	v_lshl_add_u64 v[182:183], v[182:183], 0, s[8:9]
	s_waitcnt lgkmcnt(1)
	global_store_dwordx4 v[182:183], v[40:43], off
	v_lshl_add_u64 v[182:183], v[182:183], 0, s[8:9]
	s_waitcnt lgkmcnt(0)
	global_store_dwordx4 v[182:183], v[44:47], off
	v_lshl_add_u64 v[182:183], v[182:183], 0, s[8:9]
	v_pk_mul_f32 v[16:17], v[16:17], v[230:231] op_sel_hi:[1,0]
	v_pk_mul_f32 v[0:1], v[0:1], v[230:231] op_sel_hi:[1,0]
	s_waitcnt vmcnt(11)
	v_lshlrev_b32_e32 v198, 16, v234
	v_lshlrev_b32_e32 v199, 16, v235
	v_and_b32_e32 v234, 0xffff0000, v234
	v_and_b32_e32 v235, 0xffff0000, v235
	v_pk_mul_f32 v[200:201], v[0:1], v[234:235]
	v_pk_mul_f32 v[0:1], v[0:1], v[198:199]
	v_pk_fma_f32 v[200:201], v[16:17], v[198:199], v[200:201] neg_lo:[0,0,1] neg_hi:[0,0,1]
	v_pk_fma_f32 v[0:1], v[16:17], v[234:235], v[0:1]
	v_pk_mul_f32 v[18:19], v[18:19], v[230:231] op_sel_hi:[1,0]
	v_pk_mul_f32 v[2:3], v[2:3], v[230:231] op_sel_hi:[1,0]
	v_lshlrev_b32_e32 v198, 16, v236
	v_lshlrev_b32_e32 v199, 16, v237
	v_and_b32_e32 v236, 0xffff0000, v236
	v_and_b32_e32 v237, 0xffff0000, v237
	v_pk_mul_f32 v[176:177], v[2:3], v[236:237]
	v_pk_mul_f32 v[2:3], v[2:3], v[198:199]
	v_pk_fma_f32 v[176:177], v[18:19], v[198:199], v[176:177] neg_lo:[0,0,1] neg_hi:[0,0,1]
	v_pk_fma_f32 v[2:3], v[18:19], v[236:237], v[2:3]
	v_pk_mul_f32 v[20:21], v[20:21], v[230:231] op_sel_hi:[1,0]
	v_pk_mul_f32 v[4:5], v[4:5], v[230:231] op_sel_hi:[1,0]
	s_waitcnt vmcnt(10)
	v_lshlrev_b32_e32 v198, 16, v238
	v_lshlrev_b32_e32 v199, 16, v239
	v_and_b32_e32 v238, 0xffff0000, v238
	v_and_b32_e32 v239, 0xffff0000, v239
	v_pk_mul_f32 v[178:179], v[4:5], v[238:239]
	v_pk_mul_f32 v[4:5], v[4:5], v[198:199]
	v_pk_fma_f32 v[178:179], v[20:21], v[198:199], v[178:179] neg_lo:[0,0,1] neg_hi:[0,0,1]
	v_pk_fma_f32 v[4:5], v[20:21], v[238:239], v[4:5]
	v_pk_mul_f32 v[22:23], v[22:23], v[230:231] op_sel_hi:[1,0]
	v_pk_mul_f32 v[6:7], v[6:7], v[230:231] op_sel_hi:[1,0]
	v_lshlrev_b32_e32 v198, 16, v240
	v_lshlrev_b32_e32 v199, 16, v241
	v_and_b32_e32 v240, 0xffff0000, v240
	v_and_b32_e32 v241, 0xffff0000, v241
	v_pk_mul_f32 v[180:181], v[6:7], v[240:241]
	v_pk_mul_f32 v[6:7], v[6:7], v[198:199]
	v_pk_fma_f32 v[180:181], v[22:23], v[198:199], v[180:181] neg_lo:[0,0,1] neg_hi:[0,0,1]
	v_pk_fma_f32 v[6:7], v[22:23], v[240:241], v[6:7]
	v_cvt_pk_bf16_f32 v16, v200, v201
	v_cvt_pk_bf16_f32 v17, v176, v177
	v_cvt_pk_bf16_f32 v18, v178, v179
	v_cvt_pk_bf16_f32 v19, v180, v181
	v_cvt_pk_bf16_f32 v20, v0, v1
	v_cvt_pk_bf16_f32 v21, v2, v3
	v_cvt_pk_bf16_f32 v22, v4, v5
	v_cvt_pk_bf16_f32 v23, v6, v7
	ds_write_b64 v184, v[16:17]
	ds_write_b64 v184, v[18:19] offset:16
	ds_write_b64 v184, v[20:21] offset:64
	ds_write_b64 v184, v[22:23] offset:80
	v_pk_mul_f32 v[24:25], v[24:25], v[230:231] op_sel_hi:[1,0]
	v_pk_mul_f32 v[8:9], v[8:9], v[230:231] op_sel_hi:[1,0]
	s_waitcnt vmcnt(9)
	v_lshlrev_b32_e32 v198, 16, v242
	v_lshlrev_b32_e32 v199, 16, v243
	v_and_b32_e32 v242, 0xffff0000, v242
	v_and_b32_e32 v243, 0xffff0000, v243
	v_pk_mul_f32 v[200:201], v[8:9], v[242:243]
	v_pk_mul_f32 v[8:9], v[8:9], v[198:199]
	v_pk_fma_f32 v[200:201], v[24:25], v[198:199], v[200:201] neg_lo:[0,0,1] neg_hi:[0,0,1]
	v_pk_fma_f32 v[8:9], v[24:25], v[242:243], v[8:9]
	v_pk_mul_f32 v[26:27], v[26:27], v[230:231] op_sel_hi:[1,0]
	v_pk_mul_f32 v[10:11], v[10:11], v[230:231] op_sel_hi:[1,0]
	v_lshlrev_b32_e32 v198, 16, v244
	v_lshlrev_b32_e32 v199, 16, v245
	v_and_b32_e32 v244, 0xffff0000, v244
	v_and_b32_e32 v245, 0xffff0000, v245
	v_pk_mul_f32 v[176:177], v[10:11], v[244:245]
	v_pk_mul_f32 v[10:11], v[10:11], v[198:199]
	v_pk_fma_f32 v[176:177], v[26:27], v[198:199], v[176:177] neg_lo:[0,0,1] neg_hi:[0,0,1]
	v_pk_fma_f32 v[10:11], v[26:27], v[244:245], v[10:11]
	v_pk_mul_f32 v[28:29], v[28:29], v[230:231] op_sel_hi:[1,0]
	v_pk_mul_f32 v[12:13], v[12:13], v[230:231] op_sel_hi:[1,0]
	s_waitcnt vmcnt(8)
	v_lshlrev_b32_e32 v198, 16, v246
	v_lshlrev_b32_e32 v199, 16, v247
	v_and_b32_e32 v246, 0xffff0000, v246
	v_and_b32_e32 v247, 0xffff0000, v247
	v_pk_mul_f32 v[178:179], v[12:13], v[246:247]
	v_pk_mul_f32 v[12:13], v[12:13], v[198:199]
	v_pk_fma_f32 v[178:179], v[28:29], v[198:199], v[178:179] neg_lo:[0,0,1] neg_hi:[0,0,1]
	v_pk_fma_f32 v[12:13], v[28:29], v[246:247], v[12:13]
	v_pk_mul_f32 v[30:31], v[30:31], v[230:231] op_sel_hi:[1,0]
	v_pk_mul_f32 v[14:15], v[14:15], v[230:231] op_sel_hi:[1,0]
	v_lshlrev_b32_e32 v198, 16, v248
	v_lshlrev_b32_e32 v199, 16, v249
	v_and_b32_e32 v248, 0xffff0000, v248
	v_and_b32_e32 v249, 0xffff0000, v249
	v_pk_mul_f32 v[180:181], v[14:15], v[248:249]
	v_pk_mul_f32 v[14:15], v[14:15], v[198:199]
	v_pk_fma_f32 v[180:181], v[30:31], v[198:199], v[180:181] neg_lo:[0,0,1] neg_hi:[0,0,1]
	v_pk_fma_f32 v[14:15], v[30:31], v[248:249], v[14:15]
	v_cvt_pk_bf16_f32 v24, v200, v201
	v_cvt_pk_bf16_f32 v25, v176, v177
	v_cvt_pk_bf16_f32 v26, v178, v179
	v_cvt_pk_bf16_f32 v27, v180, v181
	v_cvt_pk_bf16_f32 v28, v8, v9
	v_cvt_pk_bf16_f32 v29, v10, v11
	v_cvt_pk_bf16_f32 v30, v12, v13
	v_cvt_pk_bf16_f32 v31, v14, v15
	ds_write_b64 v184, v[24:25] offset:32
	ds_write_b64 v184, v[26:27] offset:48
	ds_write_b64 v184, v[28:29] offset:96
	ds_write_b64 v184, v[30:31] offset:112
	ds_read_b128 v[0:3], v186
	ds_read_b128 v[4:7], v186 offset:1152
	ds_read_b128 v[8:11], v186 offset:2304
	ds_read_b128 v[12:15], v186 offset:3456
	s_waitcnt lgkmcnt(3)
	global_store_dwordx4 v[182:183], v[0:3], off
	v_lshl_add_u64 v[182:183], v[182:183], 0, s[8:9]
	s_waitcnt lgkmcnt(2)
	global_store_dwordx4 v[182:183], v[4:7], off
	v_lshl_add_u64 v[182:183], v[182:183], 0, s[8:9]
	s_waitcnt lgkmcnt(1)
	global_store_dwordx4 v[182:183], v[8:11], off
	v_lshl_add_u64 v[182:183], v[182:183], 0, s[8:9]
	s_waitcnt lgkmcnt(0)
	global_store_dwordx4 v[182:183], v[12:15], off
	v_lshl_add_u64 v[182:183], v[182:183], 0, s[8:9]
	s_branch .LBB0_290
.Lep1_plain:
	s_waitcnt vmcnt(3)
	v_pk_mul_f32 v[112:113], v[112:113], v[218:219] op_sel_hi:[1,0]
	v_pk_mul_f32 v[114:115], v[114:115], v[218:219] op_sel_hi:[1,0]
	v_pk_mul_f32 v[116:117], v[116:117], v[218:219] op_sel_hi:[1,0]
	v_pk_mul_f32 v[118:119], v[118:119], v[218:219] op_sel_hi:[1,0]
	v_pk_mul_f32 v[120:121], v[120:121], v[218:219] op_sel_hi:[1,0]
	v_pk_mul_f32 v[122:123], v[122:123], v[218:219] op_sel_hi:[1,0]
	v_pk_mul_f32 v[124:125], v[124:125], v[218:219] op_sel_hi:[1,0]
	v_pk_mul_f32 v[126:127], v[126:127], v[218:219] op_sel_hi:[1,0]
	v_cvt_pk_bf16_f32 v112, v112, v113
	v_cvt_pk_bf16_f32 v113, v114, v115
	v_cvt_pk_bf16_f32 v114, v116, v117
	v_cvt_pk_bf16_f32 v115, v118, v119
	v_cvt_pk_bf16_f32 v116, v120, v121
	v_cvt_pk_bf16_f32 v117, v122, v123
	v_cvt_pk_bf16_f32 v118, v124, v125
	v_cvt_pk_bf16_f32 v119, v126, v127
	ds_write_b64 v184, v[112:113]
	ds_write_b64 v184, v[114:115] offset:16
	ds_write_b64 v184, v[116:117] offset:32
	ds_write_b64 v184, v[118:119] offset:48
	v_pk_mul_f32 v[96:97], v[96:97], v[218:219] op_sel_hi:[1,0]
	v_pk_mul_f32 v[98:99], v[98:99], v[218:219] op_sel_hi:[1,0]
	v_pk_mul_f32 v[100:101], v[100:101], v[218:219] op_sel_hi:[1,0]
	v_pk_mul_f32 v[102:103], v[102:103], v[218:219] op_sel_hi:[1,0]
	v_pk_mul_f32 v[104:105], v[104:105], v[218:219] op_sel_hi:[1,0]
	v_pk_mul_f32 v[106:107], v[106:107], v[218:219] op_sel_hi:[1,0]
	v_pk_mul_f32 v[108:109], v[108:109], v[218:219] op_sel_hi:[1,0]
	v_pk_mul_f32 v[110:111], v[110:111], v[218:219] op_sel_hi:[1,0]
	v_cvt_pk_bf16_f32 v96, v96, v97
	v_cvt_pk_bf16_f32 v97, v98, v99
	v_cvt_pk_bf16_f32 v98, v100, v101
	v_cvt_pk_bf16_f32 v99, v102, v103
	v_cvt_pk_bf16_f32 v100, v104, v105
	v_cvt_pk_bf16_f32 v101, v106, v107
	v_cvt_pk_bf16_f32 v102, v108, v109
	v_cvt_pk_bf16_f32 v103, v110, v111
	ds_write_b64 v184, v[96:97] offset:64
	ds_write_b64 v184, v[98:99] offset:80
	ds_write_b64 v184, v[100:101] offset:96
	ds_write_b64 v184, v[102:103] offset:112
	ds_read_b128 v[120:123], v186
	ds_read_b128 v[124:127], v186 offset:1152
	ds_read_b128 v[104:107], v186 offset:2304
	ds_read_b128 v[108:111], v186 offset:3456
	s_waitcnt lgkmcnt(3)
	global_store_dwordx4 v[182:183], v[120:123], off
	v_lshl_add_u64 v[182:183], v[182:183], 0, s[8:9]
	s_waitcnt lgkmcnt(2)
	global_store_dwordx4 v[182:183], v[124:127], off
	v_lshl_add_u64 v[182:183], v[182:183], 0, s[8:9]
	s_waitcnt lgkmcnt(1)
	global_store_dwordx4 v[182:183], v[104:107], off
	v_lshl_add_u64 v[182:183], v[182:183], 0, s[8:9]
	s_waitcnt lgkmcnt(0)
	global_store_dwordx4 v[182:183], v[108:111], off
	v_lshl_add_u64 v[182:183], v[182:183], 0, s[8:9]
	s_waitcnt vmcnt(6)
	v_pk_mul_f32 v[80:81], v[80:81], v[220:221] op_sel_hi:[1,0]
	v_pk_mul_f32 v[82:83], v[82:83], v[220:221] op_sel_hi:[1,0]
	v_pk_mul_f32 v[84:85], v[84:85], v[220:221] op_sel_hi:[1,0]
	v_pk_mul_f32 v[86:87], v[86:87], v[220:221] op_sel_hi:[1,0]
	v_pk_mul_f32 v[88:89], v[88:89], v[220:221] op_sel_hi:[1,0]
	v_pk_mul_f32 v[90:91], v[90:91], v[220:221] op_sel_hi:[1,0]
	v_pk_mul_f32 v[92:93], v[92:93], v[220:221] op_sel_hi:[1,0]
	v_pk_mul_f32 v[94:95], v[94:95], v[220:221] op_sel_hi:[1,0]
	v_cvt_pk_bf16_f32 v80, v80, v81
	v_cvt_pk_bf16_f32 v81, v82, v83
	v_cvt_pk_bf16_f32 v82, v84, v85
	v_cvt_pk_bf16_f32 v83, v86, v87
	v_cvt_pk_bf16_f32 v84, v88, v89
	v_cvt_pk_bf16_f32 v85, v90, v91
	v_cvt_pk_bf16_f32 v86, v92, v93
	v_cvt_pk_bf16_f32 v87, v94, v95
	ds_write_b64 v184, v[80:81]
	ds_write_b64 v184, v[82:83] offset:16
	ds_write_b64 v184, v[84:85] offset:32
	ds_write_b64 v184, v[86:87] offset:48
	v_pk_mul_f32 v[64:65], v[64:65], v[220:221] op_sel_hi:[1,0]
	v_pk_mul_f32 v[66:67], v[66:67], v[220:221] op_sel_hi:[1,0]
	v_pk_mul_f32 v[68:69], v[68:69], v[220:221] op_sel_hi:[1,0]
	v_pk_mul_f32 v[70:71], v[70:71], v[220:221] op_sel_hi:[1,0]
	v_pk_mul_f32 v[72:73], v[72:73], v[220:221] op_sel_hi:[1,0]
	v_pk_mul_f32 v[74:75], v[74:75], v[220:221] op_sel_hi:[1,0]
	v_pk_mul_f32 v[76:77], v[76:77], v[220:221] op_sel_hi:[1,0]
	v_pk_mul_f32 v[78:79], v[78:79], v[220:221] op_sel_hi:[1,0]
	v_cvt_pk_bf16_f32 v64, v64, v65
	v_cvt_pk_bf16_f32 v65, v66, v67
	v_cvt_pk_bf16_f32 v66, v68, v69
	v_cvt_pk_bf16_f32 v67, v70, v71
	v_cvt_pk_bf16_f32 v68, v72, v73
	v_cvt_pk_bf16_f32 v69, v74, v75
	v_cvt_pk_bf16_f32 v70, v76, v77
	v_cvt_pk_bf16_f32 v71, v78, v79
	ds_write_b64 v184, v[64:65] offset:64
	ds_write_b64 v184, v[66:67] offset:80
	ds_write_b64 v184, v[68:69] offset:96
	ds_write_b64 v184, v[70:71] offset:112
	ds_read_b128 v[88:91], v186
	ds_read_b128 v[92:95], v186 offset:1152
	ds_read_b128 v[72:75], v186 offset:2304
	ds_read_b128 v[76:79], v186 offset:3456
	s_waitcnt lgkmcnt(3)
	global_store_dwordx4 v[182:183], v[88:91], off
	v_lshl_add_u64 v[182:183], v[182:183], 0, s[8:9]
	s_waitcnt lgkmcnt(2)
	global_store_dwordx4 v[182:183], v[92:95], off
	v_lshl_add_u64 v[182:183], v[182:183], 0, s[8:9]
	s_waitcnt lgkmcnt(1)
	global_store_dwordx4 v[182:183], v[72:75], off
	v_lshl_add_u64 v[182:183], v[182:183], 0, s[8:9]
	s_waitcnt lgkmcnt(0)
	global_store_dwordx4 v[182:183], v[76:79], off
	v_lshl_add_u64 v[182:183], v[182:183], 0, s[8:9]
	s_waitcnt vmcnt(9)
	v_pk_mul_f32 v[48:49], v[48:49], v[228:229] op_sel_hi:[1,0]
	v_pk_mul_f32 v[50:51], v[50:51], v[228:229] op_sel_hi:[1,0]
	v_pk_mul_f32 v[52:53], v[52:53], v[228:229] op_sel_hi:[1,0]
	v_pk_mul_f32 v[54:55], v[54:55], v[228:229] op_sel_hi:[1,0]
	v_pk_mul_f32 v[56:57], v[56:57], v[228:229] op_sel_hi:[1,0]
	v_pk_mul_f32 v[58:59], v[58:59], v[228:229] op_sel_hi:[1,0]
	v_pk_mul_f32 v[60:61], v[60:61], v[228:229] op_sel_hi:[1,0]
	v_pk_mul_f32 v[62:63], v[62:63], v[228:229] op_sel_hi:[1,0]
	v_cvt_pk_bf16_f32 v48, v48, v49
	v_cvt_pk_bf16_f32 v49, v50, v51
	v_cvt_pk_bf16_f32 v50, v52, v53
	v_cvt_pk_bf16_f32 v51, v54, v55
	v_cvt_pk_bf16_f32 v52, v56, v57
	v_cvt_pk_bf16_f32 v53, v58, v59
	v_cvt_pk_bf16_f32 v54, v60, v61
	v_cvt_pk_bf16_f32 v55, v62, v63
	ds_write_b64 v184, v[48:49]
	ds_write_b64 v184, v[50:51] offset:16
	ds_write_b64 v184, v[52:53] offset:32
	ds_write_b64 v184, v[54:55] offset:48
	v_pk_mul_f32 v[32:33], v[32:33], v[228:229] op_sel_hi:[1,0]
	v_pk_mul_f32 v[34:35], v[34:35], v[228:229] op_sel_hi:[1,0]
	v_pk_mul_f32 v[36:37], v[36:37], v[228:229] op_sel_hi:[1,0]
	v_pk_mul_f32 v[38:39], v[38:39], v[228:229] op_sel_hi:[1,0]
	v_pk_mul_f32 v[40:41], v[40:41], v[228:229] op_sel_hi:[1,0]
	v_pk_mul_f32 v[42:43], v[42:43], v[228:229] op_sel_hi:[1,0]
	v_pk_mul_f32 v[44:45], v[44:45], v[228:229] op_sel_hi:[1,0]
	v_pk_mul_f32 v[46:47], v[46:47], v[228:229] op_sel_hi:[1,0]
	v_cvt_pk_bf16_f32 v32, v32, v33
	v_cvt_pk_bf16_f32 v33, v34, v35
	v_cvt_pk_bf16_f32 v34, v36, v37
	v_cvt_pk_bf16_f32 v35, v38, v39
	v_cvt_pk_bf16_f32 v36, v40, v41
	v_cvt_pk_bf16_f32 v37, v42, v43
	v_cvt_pk_bf16_f32 v38, v44, v45
	v_cvt_pk_bf16_f32 v39, v46, v47
	ds_write_b64 v184, v[32:33] offset:64
	ds_write_b64 v184, v[34:35] offset:80
	ds_write_b64 v184, v[36:37] offset:96
	ds_write_b64 v184, v[38:39] offset:112
	ds_read_b128 v[56:59], v186
	ds_read_b128 v[60:63], v186 offset:1152
	ds_read_b128 v[40:43], v186 offset:2304
	ds_read_b128 v[44:47], v186 offset:3456
	s_waitcnt lgkmcnt(3)
	global_store_dwordx4 v[182:183], v[56:59], off
	v_lshl_add_u64 v[182:183], v[182:183], 0, s[8:9]
	s_waitcnt lgkmcnt(2)
	global_store_dwordx4 v[182:183], v[60:63], off
	v_lshl_add_u64 v[182:183], v[182:183], 0, s[8:9]
	s_waitcnt lgkmcnt(1)
	global_store_dwordx4 v[182:183], v[40:43], off
	v_lshl_add_u64 v[182:183], v[182:183], 0, s[8:9]
	s_waitcnt lgkmcnt(0)
	global_store_dwordx4 v[182:183], v[44:47], off
	v_lshl_add_u64 v[182:183], v[182:183], 0, s[8:9]
	s_waitcnt vmcnt(12)
	v_pk_mul_f32 v[16:17], v[16:17], v[230:231] op_sel_hi:[1,0]
	v_pk_mul_f32 v[18:19], v[18:19], v[230:231] op_sel_hi:[1,0]
	v_pk_mul_f32 v[20:21], v[20:21], v[230:231] op_sel_hi:[1,0]
	v_pk_mul_f32 v[22:23], v[22:23], v[230:231] op_sel_hi:[1,0]
	v_pk_mul_f32 v[24:25], v[24:25], v[230:231] op_sel_hi:[1,0]
	v_pk_mul_f32 v[26:27], v[26:27], v[230:231] op_sel_hi:[1,0]
	v_pk_mul_f32 v[28:29], v[28:29], v[230:231] op_sel_hi:[1,0]
	v_pk_mul_f32 v[30:31], v[30:31], v[230:231] op_sel_hi:[1,0]
	v_cvt_pk_bf16_f32 v16, v16, v17
	v_cvt_pk_bf16_f32 v17, v18, v19
	v_cvt_pk_bf16_f32 v18, v20, v21
	v_cvt_pk_bf16_f32 v19, v22, v23
	v_cvt_pk_bf16_f32 v20, v24, v25
	v_cvt_pk_bf16_f32 v21, v26, v27
	v_cvt_pk_bf16_f32 v22, v28, v29
	v_cvt_pk_bf16_f32 v23, v30, v31
	ds_write_b64 v184, v[16:17]
	ds_write_b64 v184, v[18:19] offset:16
	ds_write_b64 v184, v[20:21] offset:32
	ds_write_b64 v184, v[22:23] offset:48
	v_pk_mul_f32 v[0:1], v[0:1], v[230:231] op_sel_hi:[1,0]
	v_pk_mul_f32 v[2:3], v[2:3], v[230:231] op_sel_hi:[1,0]
	v_pk_mul_f32 v[4:5], v[4:5], v[230:231] op_sel_hi:[1,0]
	v_pk_mul_f32 v[6:7], v[6:7], v[230:231] op_sel_hi:[1,0]
	v_pk_mul_f32 v[8:9], v[8:9], v[230:231] op_sel_hi:[1,0]
	v_pk_mul_f32 v[10:11], v[10:11], v[230:231] op_sel_hi:[1,0]
	v_pk_mul_f32 v[12:13], v[12:13], v[230:231] op_sel_hi:[1,0]
	v_pk_mul_f32 v[14:15], v[14:15], v[230:231] op_sel_hi:[1,0]
	v_cvt_pk_bf16_f32 v0, v0, v1
	v_cvt_pk_bf16_f32 v1, v2, v3
	v_cvt_pk_bf16_f32 v2, v4, v5
	v_cvt_pk_bf16_f32 v3, v6, v7
	v_cvt_pk_bf16_f32 v4, v8, v9
	v_cvt_pk_bf16_f32 v5, v10, v11
	v_cvt_pk_bf16_f32 v6, v12, v13
	v_cvt_pk_bf16_f32 v7, v14, v15
	ds_write_b64 v184, v[0:1] offset:64
	ds_write_b64 v184, v[2:3] offset:80
	ds_write_b64 v184, v[4:5] offset:96
	ds_write_b64 v184, v[6:7] offset:112
	ds_read_b128 v[24:27], v186
	ds_read_b128 v[28:31], v186 offset:1152
	ds_read_b128 v[8:11], v186 offset:2304
	ds_read_b128 v[12:15], v186 offset:3456
	s_waitcnt lgkmcnt(3)
	global_store_dwordx4 v[182:183], v[24:27], off
	v_lshl_add_u64 v[182:183], v[182:183], 0, s[8:9]
	s_waitcnt lgkmcnt(2)
	global_store_dwordx4 v[182:183], v[28:31], off
	v_lshl_add_u64 v[182:183], v[182:183], 0, s[8:9]
	s_waitcnt lgkmcnt(1)
	global_store_dwordx4 v[182:183], v[8:11], off
	v_lshl_add_u64 v[182:183], v[182:183], 0, s[8:9]
	s_waitcnt lgkmcnt(0)
	global_store_dwordx4 v[182:183], v[12:15], off
	v_lshl_add_u64 v[182:183], v[182:183], 0, s[8:9]

.LBB0_844:
	s_or_b64 exec, exec, s[16:17]
	s_waitcnt lgkmcnt(0)
	s_barrier
	ds_read_b32 v133, v154 offset:2048
	s_mov_b32 s14, 0x800000
	v_lshlrev_b64 v[144:145], 10, v[130:131]
	v_lshlrev_b64 v[130:131], 11, v[130:131]
	v_cndmask_b32_e64 v132, 8, 0, s[8:9]
	s_waitcnt lgkmcnt(0)
	v_fmamk_f32 v133, v133, 0x3a800000, v224
	v_cmp_gt_f32_e32 vcc, s14, v133
	v_mul_f32_e32 v140, 0x4b800000, v133
	v_lshl_add_u64 v[130:131], s[26:27], 0, v[130:131]
	v_cndmask_b32_e32 v133, v133, v140, vcc
	v_rsq_f32_e32 v133, v133
	v_lshl_add_u64 v[130:131], v[128:129], 1, v[130:131]
	v_lshlrev_b32_e32 v132, 1, v132
	v_lshl_add_u64 v[142:143], v[128:129], 2, s[24:25]
	v_mul_f32_e32 v140, 0x45800000, v133
	v_cndmask_b32_e32 v140, v133, v140, vcc
	v_mov_b32_e32 v133, v193
	v_lshl_add_u64 v[146:147], v[130:131], 0, v[132:133]
	v_lshlrev_b32_e32 v192, 2, v141
	v_lshl_add_u64 v[130:131], v[142:143], 0, v[192:193]
	v_readlane_b32 vcc_lo, v253, 47
	v_readlane_b32 vcc_hi, v253, 48
	s_nop 1
	s_and_b64 vcc, exec, vcc
	s_movk_i32 s100, 0x90
	s_cselect_b32 s100, 0x110, s100
	s_movk_i32 s101, 0x1200
	s_cselect_b32 s101, 0x2200, s101
	v_lshrrev_b32_e32 v164, 6, v250
	v_mul_lo_u32 v164, v164, s101
	v_and_b32_e32 v165, 31, v250
	v_mul_lo_u32 v165, v165, s100
	v_add_u32_e32 v166, v164, v165
	v_add_u32_e32 v166, 0x1000, v166
	v_bfe_u32 v165, v250, 5, 1
	v_lshl_add_u32 v166, v165, 4, v166
	s_cselect_b32 s100, 4, 3
	v_lshrrev_b32_e32 v164, s100, v225
	s_cselect_b32 s100, 12, 11
	v_lshlrev_b32_e32 v164, s100, v164
	s_cselect_b32 s100, 15, 7
	v_and_b32_e32 v165, s100, v225
	v_lshl_or_b32 v169, v165, 4, v164
	s_mov_b64 s[100:101], 0x10000
	global_load_dwordx4 v[202:205], v[130:131], off
	global_load_dwordx4 v[206:209], v[130:131], off offset:32
	global_load_dwordx4 v[210:213], v[130:131], off offset:64
	global_load_dwordx4 v[214:217], v[130:131], off offset:96
	global_load_dwordx4 v[234:237], v[130:131], off offset:128
	global_load_dwordx4 v[238:241], v[130:131], off offset:160
	global_load_dwordx4 v[242:245], v[130:131], off offset:192
	global_load_dwordx4 v[246:249], v[130:131], off offset:224
	global_load_dwordx4 v[170:173], v[146:147], off
	global_load_dwordx4 v[174:177], v[146:147], off offset:32
	global_load_dwordx4 v[178:181], v[146:147], off offset:64
	global_load_dwordx4 v[182:185], v[146:147], off offset:96
	v_lshl_add_u64 v[164:165], v[146:147], 0, s[100:101]
	global_load_dwordx4 v[218:221], v[164:165], off
	global_load_dwordx4 v[228:231], v[164:165], off offset:32
	global_load_dwordx4 v[186:189], v[164:165], off offset:64
	global_load_dwordx4 v[198:201], v[164:165], off offset:96
	v_lshl_add_u64 v[190:191], v[164:165], 0, s[100:101]
	v_lshl_add_u64 v[164:165], v[190:191], 0, s[100:101]
	s_waitcnt vmcnt(0)
	v_mov_b64_e32 v[156:157], v[170:171]
	v_mov_b64_e32 v[158:159], v[172:173]
	v_readlane_b32 s16, v253, 47
	v_readlane_b32 s36, v252, 2
	v_pk_mul_f32 v[112:113], v[112:113], v[140:141] op_sel_hi:[1,0]
	v_pk_mul_f32 v[114:115], v[114:115], v[140:141] op_sel_hi:[1,0]
	v_readlane_b32 s17, v253, 48
	v_readlane_b32 s37, v252, 3
	s_mov_b64 s[14:15], -1
	s_and_b64 vcc, exec, s[16:17]
	v_readlane_b32 s38, v252, 4
	v_readlane_b32 s39, v252, 5
	v_readlane_b32 s40, v252, 6
	v_readlane_b32 s41, v252, 7
	v_readlane_b32 s42, v252, 8
	v_readlane_b32 s43, v252, 9
	s_waitcnt lgkmcnt(0)
	v_mov_b32_e32 v133, v158
	v_mov_b32_e32 v155, v159
	v_mov_b64_e32 v[158:159], v[202:203]
	v_mov_b64_e32 v[160:161], v[204:205]
	v_permlane32_swap_b32_e32 v156, v133
	v_permlane32_swap_b32_e32 v157, v155
	v_lshlrev_b32_e32 v142, 16, v156
	v_and_b32_e32 v143, 0xffff0000, v156
	v_lshlrev_b32_e32 v156, 16, v157
	v_and_b32_e32 v157, 0xffff0000, v157
	s_nop 0
	v_pk_fma_f32 v[112:113], v[158:159], v[112:113], v[142:143]
	v_pk_fma_f32 v[114:115], v[160:161], v[114:115], v[156:157]
	v_lshl_add_u64 v[142:143], v[144:145], 2, s[36:37]
	s_cbranch_vccz .LBB0_846
	v_lshl_add_u64 v[156:157], v[128:129], 2, v[142:143]
	v_lshl_add_u64 v[156:157], v[156:157], 0, v[192:193]
	s_mov_b64 s[14:15], 0
	s_nop 0
	v_readfirstlane_b32 s100, v156
	v_readfirstlane_b32 s101, v157
	ds_write_b128 v166, v[112:115]

.LBB0_848:
	v_mov_b64_e32 v[156:157], v[206:207]
	v_mov_b64_e32 v[158:159], v[208:209]
	v_readlane_b32 s36, v253, 47
	v_mov_b32_e32 v141, v140
	v_readlane_b32 s37, v253, 48
	v_lshlrev_b32_e32 v160, 16, v133
	v_and_b32_e32 v161, 0xffff0000, v133
	v_lshlrev_b32_e32 v162, 16, v155
	v_and_b32_e32 v163, 0xffff0000, v155
	v_pk_mul_f32 v[116:117], v[116:117], v[140:141]
	v_pk_mul_f32 v[118:119], v[118:119], v[140:141]
	v_cndmask_b32_e64 v133, 0, 1, s[36:37]
	s_mov_b64 s[14:15], -1
	v_cmp_ne_u32_e64 s[16:17], 1, v133
	s_andn2_b64 vcc, exec, s[36:37]
	s_nop 0
	v_pk_fma_f32 v[116:117], v[116:117], v[156:157], v[160:161]
	v_pk_fma_f32 v[118:119], v[118:119], v[158:159], v[162:163]
	s_cbranch_vccnz .LBB0_850
	v_lshl_add_u64 v[156:157], v[128:129], 2, v[142:143]
	v_lshl_add_u64 v[156:157], v[156:157], 0, v[192:193]
	s_mov_b64 s[14:15], 0
	ds_write_b128 v166, v[116:119] offset:32

.LBB0_852:
	v_readlane_b32 s36, v253, 25
	v_readlane_b32 s37, v253, 26
	s_andn2_b64 vcc, exec, s[36:37]
	s_nop 0
	v_cndmask_b32_e64 v133, 0, 1, s[36:37]
	v_cmp_ne_u32_e64 s[14:15], 1, v133
	s_cbranch_vccnz .LBB0_854
	v_cvt_pk_bf16_f32 v112, v112, v113
	v_cvt_pk_bf16_f32 v113, v114, v115
	v_cvt_pk_bf16_f32 v114, v116, v117
	v_cvt_pk_bf16_f32 v115, v118, v119
	s_nop 0
	v_permlane32_swap_b32_e32 v112, v114
	v_permlane32_swap_b32_e32 v113, v115
	s_nop 0
	v_readfirstlane_b32 s100, v146
	v_readfirstlane_b32 s101, v147
	ds_write_b128 v166, v[112:115]
.LBB0_854:
	s_nop 1
	v_lshl_add_u64 v[112:113], v[144:145], 1, s[0:1]
	v_lshl_add_u64 v[144:145], v[128:129], 1, v[112:113]
	v_mov_b32_e32 v133, v193
	v_lshl_add_u64 v[146:147], v[144:145], 0, v[132:133]
	v_add_co_u32_e32 v112, vcc, 0x1dc0000, v146
	v_mov_b64_e32 v[156:157], v[210:211]
	v_mov_b64_e32 v[158:159], v[212:213]
	s_nop 0
	v_addc_co_u32_e32 v113, vcc, 0, v147, vcc
	v_mov_b64_e32 v[112:113], v[174:175]
	v_mov_b64_e32 v[114:115], v[176:177]
	s_mov_b64 s[36:37], -1
	s_and_b64 vcc, exec, s[16:17]
	s_waitcnt lgkmcnt(0)
	v_mov_b32_e32 v116, v114
	v_mov_b32_e32 v117, v115
	s_nop 0
	v_permlane32_swap_b32_e32 v112, v116
	v_permlane32_swap_b32_e32 v113, v117
	v_lshlrev_b32_e32 v114, 16, v112
	v_and_b32_e32 v115, 0xffff0000, v112
	v_lshlrev_b32_e32 v118, 16, v113
	v_and_b32_e32 v119, 0xffff0000, v113
	v_pk_mul_f32 v[112:113], v[120:121], v[140:141]
	s_nop 0
	v_pk_fma_f32 v[112:113], v[112:113], v[156:157], v[114:115]
	v_pk_mul_f32 v[114:115], v[122:123], v[140:141]
	s_nop 0
	v_pk_fma_f32 v[114:115], v[114:115], v[158:159], v[118:119]
	s_cbranch_vccnz .LBB0_856
	v_lshl_add_u64 v[118:119], v[128:129], 2, v[142:143]
	v_lshl_add_u64 v[118:119], v[118:119], 0, v[192:193]
	s_mov_b64 s[36:37], 0
	ds_write_b128 v166, v[112:115] offset:64

.LBB0_858:
	v_mov_b64_e32 v[118:119], v[214:215]
	v_mov_b64_e32 v[120:121], v[216:217]
	v_lshlrev_b32_e32 v122, 16, v116
	v_and_b32_e32 v123, 0xffff0000, v116
	v_lshlrev_b32_e32 v156, 16, v117
	v_and_b32_e32 v157, 0xffff0000, v117
	v_pk_mul_f32 v[116:117], v[124:125], v[140:141]
	v_pk_mul_f32 v[124:125], v[126:127], v[140:141]
	s_and_b64 vcc, exec, s[16:17]
	s_mov_b64 s[36:37], -1
	s_nop 0
	v_pk_fma_f32 v[116:117], v[116:117], v[118:119], v[122:123]
	v_pk_fma_f32 v[118:119], v[124:125], v[120:121], v[156:157]
	s_cbranch_vccnz .LBB0_987
	v_lshl_add_u64 v[120:121], v[128:129], 2, v[142:143]
	v_lshl_add_u64 v[120:121], v[120:121], 0, v[192:193]
	ds_write_b128 v166, v[116:119] offset:96
	s_cbranch_execz .LBB0_988

.LBB0_861:
	s_mov_b64 s[36:37], 0x1dc0020
	v_cvt_pk_bf16_f32 v112, v112, v113
	v_cvt_pk_bf16_f32 v113, v114, v115
	v_cvt_pk_bf16_f32 v114, v116, v117
	v_cvt_pk_bf16_f32 v115, v118, v119
	v_lshl_add_u64 v[120:121], v[146:147], 0, s[36:37]
	v_permlane32_swap_b32_e32 v112, v114
	v_permlane32_swap_b32_e32 v113, v115
	ds_write_b128 v166, v[112:115] offset:32
.LBB0_862:
	v_mov_b32_e32 v133, v193
	s_nop 0
	v_lshl_add_u64 v[112:113], v[144:145], 0, v[132:133]
	v_add_co_u32_e32 v114, vcc, 0x1dc0000, v112
	v_pk_mul_f32 v[96:97], v[96:97], v[140:141]
	s_nop 0
	v_addc_co_u32_e32 v115, vcc, 0, v113, vcc
	v_mov_b64_e32 v[116:117], v[178:179]
	v_mov_b64_e32 v[118:119], v[180:181]
	v_pk_mul_f32 v[98:99], v[98:99], v[140:141]
	s_mov_b64 s[36:37], -1
	s_and_b64 vcc, exec, s[16:17]
	s_waitcnt lgkmcnt(0)
	v_mov_b32_e32 v114, v118
	v_mov_b32_e32 v115, v119
	v_mov_b64_e32 v[118:119], v[234:235]
	v_mov_b64_e32 v[120:121], v[236:237]
	v_permlane32_swap_b32_e32 v116, v114
	v_permlane32_swap_b32_e32 v117, v115
	v_lshlrev_b32_e32 v122, 16, v116
	v_and_b32_e32 v123, 0xffff0000, v116
	v_lshlrev_b32_e32 v116, 16, v117
	v_and_b32_e32 v117, 0xffff0000, v117
	s_nop 0
	v_pk_fma_f32 v[96:97], v[96:97], v[118:119], v[122:123]
	v_pk_fma_f32 v[98:99], v[98:99], v[120:121], v[116:117]
	s_cbranch_vccnz .LBB0_864
	v_lshl_add_u64 v[116:117], v[128:129], 2, v[142:143]
	v_lshl_add_u64 v[116:117], v[116:117], 0, v[192:193]
	s_mov_b64 s[36:37], 0
	ds_write_b128 v166, v[96:99] offset:128

.LBB0_866:
	v_mov_b64_e32 v[116:117], v[238:239]
	v_mov_b64_e32 v[118:119], v[240:241]
	v_lshlrev_b32_e32 v120, 16, v114
	v_and_b32_e32 v121, 0xffff0000, v114
	v_lshlrev_b32_e32 v114, 16, v115
	v_and_b32_e32 v115, 0xffff0000, v115
	v_pk_mul_f32 v[100:101], v[100:101], v[140:141]
	v_pk_mul_f32 v[102:103], v[102:103], v[140:141]
	s_mov_b64 s[36:37], -1
	s_and_b64 vcc, exec, s[16:17]
	s_nop 0
	v_pk_fma_f32 v[100:101], v[100:101], v[116:117], v[120:121]
	v_pk_fma_f32 v[102:103], v[102:103], v[118:119], v[114:115]
	s_cbranch_vccnz .LBB0_989
	v_lshl_add_u64 v[114:115], v[128:129], 2, v[142:143]
	v_lshl_add_u64 v[114:115], v[114:115], 0, v[192:193]
	ds_write_b128 v166, v[100:103] offset:160
	s_cbranch_execz .LBB0_990

.LBB0_869:
	s_mov_b64 s[36:37], 0x1dc0040
	v_cvt_pk_bf16_f32 v96, v96, v97
	v_cvt_pk_bf16_f32 v97, v98, v99
	v_cvt_pk_bf16_f32 v98, v100, v101
	v_cvt_pk_bf16_f32 v99, v102, v103
	v_lshl_add_u64 v[112:113], v[112:113], 0, s[36:37]
	v_permlane32_swap_b32_e32 v96, v98
	v_permlane32_swap_b32_e32 v97, v99
	ds_write_b128 v166, v[96:99] offset:64
.LBB0_870:
	v_mov_b32_e32 v133, v193
	v_lshl_add_u64 v[112:113], v[144:145], 0, v[132:133]
	v_add_co_u32_e32 v96, vcc, 0x1dc0000, v112
	v_mov_b64_e32 v[114:115], v[242:243]
	v_mov_b64_e32 v[116:117], v[244:245]
	s_nop 0
	v_addc_co_u32_e32 v97, vcc, 0, v113, vcc
	v_mov_b64_e32 v[96:97], v[182:183]
	v_mov_b64_e32 v[98:99], v[184:185]
	global_load_dwordx4 v[170:173], v[190:191], off
	global_load_dwordx4 v[174:177], v[190:191], off offset:32
	global_load_dwordx4 v[178:181], v[190:191], off offset:64
	global_load_dwordx4 v[182:185], v[190:191], off offset:96
	s_mov_b64 s[36:37], -1
	s_and_b64 vcc, exec, s[16:17]
	s_waitcnt lgkmcnt(0)
	v_mov_b32_e32 v100, v98
	v_mov_b32_e32 v101, v99
	s_nop 0
	v_permlane32_swap_b32_e32 v96, v100
	v_permlane32_swap_b32_e32 v97, v101
	v_lshlrev_b32_e32 v98, 16, v96
	v_and_b32_e32 v99, 0xffff0000, v96
	v_lshlrev_b32_e32 v102, 16, v97
	v_and_b32_e32 v103, 0xffff0000, v97
	v_pk_mul_f32 v[96:97], v[104:105], v[140:141]
	s_nop 0
	v_pk_fma_f32 v[96:97], v[96:97], v[114:115], v[98:99]
	v_pk_mul_f32 v[98:99], v[106:107], v[140:141]
	s_nop 0
	v_pk_fma_f32 v[98:99], v[98:99], v[116:117], v[102:103]
	s_cbranch_vccnz .LBB0_872
	v_lshl_add_u64 v[102:103], v[128:129], 2, v[142:143]
	v_lshl_add_u64 v[102:103], v[102:103], 0, v[192:193]
	s_mov_b64 s[36:37], 0
	ds_write_b128 v166, v[96:99] offset:192

.LBB0_874:
	v_mov_b64_e32 v[102:103], v[246:247]
	v_mov_b64_e32 v[104:105], v[248:249]
	v_lshlrev_b32_e32 v106, 16, v100
	v_and_b32_e32 v107, 0xffff0000, v100
	v_lshlrev_b32_e32 v114, 16, v101
	v_and_b32_e32 v115, 0xffff0000, v101
	v_pk_mul_f32 v[100:101], v[108:109], v[140:141]
	v_pk_mul_f32 v[108:109], v[110:111], v[140:141]
	s_and_b64 vcc, exec, s[16:17]
	s_mov_b64 s[36:37], -1
	s_nop 0
	v_pk_fma_f32 v[100:101], v[100:101], v[102:103], v[106:107]
	v_pk_fma_f32 v[102:103], v[108:109], v[104:105], v[114:115]
	s_cbranch_vccnz .LBB0_991
	v_lshl_add_u64 v[104:105], v[128:129], 2, v[142:143]
	v_lshl_add_u64 v[104:105], v[104:105], 0, v[192:193]
	ds_write_b128 v166, v[100:103] offset:224
	s_cbranch_execz .LBB0_992

.LBB0_877:
	s_mov_b64 s[36:37], 0x1dc0060
	v_cvt_pk_bf16_f32 v96, v96, v97
	v_cvt_pk_bf16_f32 v97, v98, v99
	v_cvt_pk_bf16_f32 v98, v100, v101
	v_cvt_pk_bf16_f32 v99, v102, v103
	v_lshl_add_u64 v[104:105], v[112:113], 0, s[36:37]
	v_permlane32_swap_b32_e32 v96, v98
	v_permlane32_swap_b32_e32 v97, v99
	ds_write_b128 v166, v[96:99] offset:96
.LBB0_878:
	v_readlane_b32 vcc_lo, v253, 47
	v_readlane_b32 vcc_hi, v253, 48
	s_nop 1
	s_and_b64 vcc, exec, vcc
	s_cbranch_scc0 .Lof0_h
	v_lshrrev_b32_e32 v112, 6, v250
	v_mul_u32_u24_e32 v112, 0x2200, v112
	v_lshrrev_b32_e32 v113, 4, v225
	v_mul_u32_u24_e32 v113, 0x110, v113
	v_and_b32_e32 v114, 15, v225
	v_lshl_add_u32 v113, v114, 4, v113
	v_add_u32_e32 v112, v112, v113
	v_add_u32_e32 v112, 0x1000, v112
	ds_read_b128 v[96:99], v112
	ds_read_b128 v[100:103], v112 offset:1088
	ds_read_b128 v[104:107], v112 offset:2176
	ds_read_b128 v[108:111], v112 offset:3264
	s_waitcnt lgkmcnt(3)
	global_store_dwordx4 v169, v[96:99], s[100:101]
	s_add_u32 s100, s100, 0x4000
	s_addc_u32 s101, s101, 0
	s_waitcnt lgkmcnt(2)
	global_store_dwordx4 v169, v[100:103], s[100:101]
	s_add_u32 s100, s100, 0x4000
	s_addc_u32 s101, s101, 0
	s_waitcnt lgkmcnt(1)
	global_store_dwordx4 v169, v[104:107], s[100:101]
	s_add_u32 s100, s100, 0x4000
	s_addc_u32 s101, s101, 0
	s_waitcnt lgkmcnt(0)
	global_store_dwordx4 v169, v[108:111], s[100:101]
	s_add_u32 s100, s100, 0x4000
	s_addc_u32 s101, s101, 0
	ds_read_b128 v[96:99], v112 offset:4352
	ds_read_b128 v[100:103], v112 offset:5440
	ds_read_b128 v[104:107], v112 offset:6528
	ds_read_b128 v[108:111], v112 offset:7616
	s_waitcnt lgkmcnt(3)
	global_store_dwordx4 v169, v[96:99], s[100:101]
	s_add_u32 s100, s100, 0x4000
	s_addc_u32 s101, s101, 0
	s_waitcnt lgkmcnt(2)
	global_store_dwordx4 v169, v[100:103], s[100:101]
	s_add_u32 s100, s100, 0x4000
	s_addc_u32 s101, s101, 0
	s_waitcnt lgkmcnt(1)
	global_store_dwordx4 v169, v[104:107], s[100:101]
	s_add_u32 s100, s100, 0x4000
	s_addc_u32 s101, s101, 0
	s_waitcnt lgkmcnt(0)
	global_store_dwordx4 v169, v[108:111], s[100:101]
	s_add_u32 s100, s100, 0x4000
	s_addc_u32 s101, s101, 0
	s_branch .Lof0_d
.Lof0_h:
	v_lshrrev_b32_e32 v112, 6, v250
	v_mul_u32_u24_e32 v112, 0x1200, v112
	v_lshrrev_b32_e32 v113, 3, v225
	v_mul_u32_u24_e32 v113, 0x90, v113
	v_and_b32_e32 v114, 7, v225
	v_lshl_add_u32 v113, v114, 4, v113
	v_add_u32_e32 v112, v112, v113
	v_add_u32_e32 v112, 0x1000, v112
	ds_read_b128 v[96:99], v112
	ds_read_b128 v[100:103], v112 offset:1152
	ds_read_b128 v[104:107], v112 offset:2304
	ds_read_b128 v[108:111], v112 offset:3456
	s_waitcnt lgkmcnt(3)
	global_store_dwordx4 v169, v[96:99], s[100:101]
	s_add_u32 s100, s100, 0x4000
	s_addc_u32 s101, s101, 0
	s_waitcnt lgkmcnt(2)
	global_store_dwordx4 v169, v[100:103], s[100:101]
	s_add_u32 s100, s100, 0x4000
	s_addc_u32 s101, s101, 0
	s_waitcnt lgkmcnt(1)
	global_store_dwordx4 v169, v[104:107], s[100:101]
	s_add_u32 s100, s100, 0x4000
	s_addc_u32 s101, s101, 0
	s_waitcnt lgkmcnt(0)
	global_store_dwordx4 v169, v[108:111], s[100:101]
	s_add_u32 s100, s100, 0x4000
	s_addc_u32 s101, s101, 0
.Lof0_d:
	s_nop 1
	v_lshlrev_b64 v[98:99], 11, v[138:139]
	v_lshl_add_u64 v[98:99], s[26:27], 0, v[98:99]
	v_lshl_add_u64 v[98:99], v[128:129], 1, v[98:99]
	v_mov_b32_e32 v133, v193
	v_lshl_add_u64 v[102:103], v[98:99], 0, v[132:133]
	v_mov_b64_e32 v[108:109], v[218:219]
	v_mov_b64_e32 v[110:111], v[220:221]
	ds_read_b32 v96, v154 offset:2176
	s_mov_b32 s31, 0x800000
	v_readlane_b32 s40, v252, 2
	v_lshlrev_b64 v[100:101], 10, v[138:139]
	v_readlane_b32 s41, v252, 3
	s_waitcnt lgkmcnt(0)
	v_fmamk_f32 v96, v96, 0x3a800000, v224
	v_cmp_gt_f32_e32 vcc, s31, v96
	v_mul_f32_e32 v97, 0x4b800000, v96
	s_mov_b64 s[36:37], -1
	v_cndmask_b32_e32 v96, v96, v97, vcc
	v_rsq_f32_e32 v96, v96
	v_readlane_b32 s42, v252, 4
	v_readlane_b32 s43, v252, 5
	v_readlane_b32 s44, v252, 6
	v_mul_f32_e32 v97, 0x45800000, v96
	v_cndmask_b32_e32 v96, v96, v97, vcc
	v_pk_mul_f32 v[80:81], v[80:81], v[96:97] op_sel_hi:[1,0]
	v_pk_mul_f32 v[82:83], v[82:83], v[96:97] op_sel_hi:[1,0]
	s_and_b64 vcc, exec, s[16:17]
	v_readlane_b32 s45, v252, 7
	v_readlane_b32 s46, v252, 8
	v_readlane_b32 s47, v252, 9
	s_nop 0
	v_mov_b32_e32 v105, v110
	v_mov_b32_e32 v106, v111
	v_mov_b64_e32 v[110:111], v[202:203]
	v_mov_b64_e32 v[112:113], v[204:205]
	v_permlane32_swap_b32_e32 v108, v105
	v_permlane32_swap_b32_e32 v109, v106
	v_lshlrev_b32_e32 v98, 16, v108
	v_and_b32_e32 v99, 0xffff0000, v108
	v_lshlrev_b32_e32 v108, 16, v109
	v_and_b32_e32 v109, 0xffff0000, v109
	s_nop 0
	v_pk_fma_f32 v[80:81], v[110:111], v[80:81], v[98:99]
	v_pk_fma_f32 v[82:83], v[112:113], v[82:83], v[108:109]
	v_lshl_add_u64 v[98:99], v[100:101], 2, s[40:41]
	s_cbranch_vccnz .LBB0_880
	v_lshl_add_u64 v[108:109], v[128:129], 2, v[98:99]
	v_lshl_add_u64 v[108:109], v[108:109], 0, v[192:193]
	s_mov_b64 s[36:37], 0
	ds_write_b128 v166, v[80:83]

.LBB0_882:
	v_mov_b64_e32 v[108:109], v[206:207]
	v_mov_b64_e32 v[110:111], v[208:209]
	v_mov_b32_e32 v97, v96
	v_lshlrev_b32_e32 v112, 16, v105
	v_and_b32_e32 v113, 0xffff0000, v105
	v_lshlrev_b32_e32 v114, 16, v106
	v_and_b32_e32 v115, 0xffff0000, v106
	v_pk_mul_f32 v[84:85], v[84:85], v[96:97]
	v_pk_mul_f32 v[86:87], v[86:87], v[96:97]
	s_mov_b64 s[36:37], -1
	s_and_b64 vcc, exec, s[16:17]
	s_nop 0
	v_pk_fma_f32 v[84:85], v[84:85], v[108:109], v[112:113]
	v_pk_fma_f32 v[86:87], v[86:87], v[110:111], v[114:115]
	s_cbranch_vccnz .LBB0_993
	v_lshl_add_u64 v[106:107], v[128:129], 2, v[98:99]
	v_lshl_add_u64 v[106:107], v[106:107], 0, v[192:193]
	ds_write_b128 v166, v[84:87] offset:32
	s_cbranch_execz .LBB0_994

.LBB0_885:
	v_cvt_pk_bf16_f32 v80, v80, v81
	v_cvt_pk_bf16_f32 v81, v82, v83
	v_cvt_pk_bf16_f32 v82, v84, v85
	v_cvt_pk_bf16_f32 v83, v86, v87
	s_nop 0
	v_permlane32_swap_b32_e32 v80, v82
	v_permlane32_swap_b32_e32 v81, v83
	ds_write_b128 v166, v[80:83]
.LBB0_886:
	s_nop 1
	v_lshl_add_u64 v[80:81], v[100:101], 1, s[0:1]
	v_lshl_add_u64 v[100:101], v[128:129], 1, v[80:81]
	v_mov_b32_e32 v133, v193
	v_lshl_add_u64 v[102:103], v[100:101], 0, v[132:133]
	v_add_co_u32_e32 v80, vcc, 0x1dc0000, v102
	v_mov_b64_e32 v[106:107], v[210:211]
	v_mov_b64_e32 v[108:109], v[212:213]
	s_nop 0
	v_addc_co_u32_e32 v81, vcc, 0, v103, vcc
	v_mov_b64_e32 v[80:81], v[228:229]
	v_mov_b64_e32 v[82:83], v[230:231]
	s_mov_b64 s[36:37], -1
	s_and_b64 vcc, exec, s[16:17]
	s_waitcnt lgkmcnt(0)
	v_mov_b32_e32 v84, v82
	v_mov_b32_e32 v85, v83
	s_nop 0
	v_permlane32_swap_b32_e32 v80, v84
	v_permlane32_swap_b32_e32 v81, v85
	v_lshlrev_b32_e32 v82, 16, v80
	v_and_b32_e32 v83, 0xffff0000, v80
	v_lshlrev_b32_e32 v86, 16, v81
	v_and_b32_e32 v87, 0xffff0000, v81
	v_pk_mul_f32 v[80:81], v[88:89], v[96:97]
	s_nop 0
	v_pk_fma_f32 v[80:81], v[80:81], v[106:107], v[82:83]
	v_pk_mul_f32 v[82:83], v[90:91], v[96:97]
	s_nop 0
	v_pk_fma_f32 v[82:83], v[82:83], v[108:109], v[86:87]
	s_cbranch_vccnz .LBB0_888
	v_lshl_add_u64 v[86:87], v[128:129], 2, v[98:99]
	v_lshl_add_u64 v[86:87], v[86:87], 0, v[192:193]
	s_mov_b64 s[36:37], 0
	ds_write_b128 v166, v[80:83] offset:64

.LBB0_890:
	v_mov_b64_e32 v[86:87], v[214:215]
	v_mov_b64_e32 v[88:89], v[216:217]
	v_lshlrev_b32_e32 v90, 16, v84
	v_and_b32_e32 v91, 0xffff0000, v84
	v_lshlrev_b32_e32 v106, 16, v85
	v_and_b32_e32 v107, 0xffff0000, v85
	v_pk_mul_f32 v[84:85], v[92:93], v[96:97]
	v_pk_mul_f32 v[92:93], v[94:95], v[96:97]
	s_and_b64 vcc, exec, s[16:17]
	s_mov_b64 s[36:37], -1
	s_nop 0
	v_pk_fma_f32 v[84:85], v[84:85], v[86:87], v[90:91]
	v_pk_fma_f32 v[86:87], v[92:93], v[88:89], v[106:107]
	s_cbranch_vccnz .LBB0_995
	v_lshl_add_u64 v[88:89], v[128:129], 2, v[98:99]
	v_lshl_add_u64 v[88:89], v[88:89], 0, v[192:193]
	ds_write_b128 v166, v[84:87] offset:96
	s_cbranch_execz .LBB0_996

.LBB0_893:
	s_mov_b64 s[36:37], 0x1dc0020
	v_cvt_pk_bf16_f32 v80, v80, v81
	v_cvt_pk_bf16_f32 v81, v82, v83
	v_cvt_pk_bf16_f32 v82, v84, v85
	v_cvt_pk_bf16_f32 v83, v86, v87
	v_lshl_add_u64 v[88:89], v[102:103], 0, s[36:37]
	v_permlane32_swap_b32_e32 v80, v82
	v_permlane32_swap_b32_e32 v81, v83
	ds_write_b128 v166, v[80:83] offset:32
.LBB0_894:
	v_mov_b32_e32 v133, v193
	s_nop 0
	v_lshl_add_u64 v[80:81], v[100:101], 0, v[132:133]
	v_add_co_u32_e32 v82, vcc, 0x1dc0000, v80
	v_pk_mul_f32 v[64:65], v[64:65], v[96:97]
	s_nop 0
	v_addc_co_u32_e32 v83, vcc, 0, v81, vcc
	v_mov_b64_e32 v[84:85], v[186:187]
	v_mov_b64_e32 v[86:87], v[188:189]
	v_pk_mul_f32 v[66:67], v[66:67], v[96:97]
	s_mov_b64 s[36:37], -1
	s_and_b64 vcc, exec, s[16:17]
	s_waitcnt lgkmcnt(0)
	v_mov_b32_e32 v82, v86
	v_mov_b32_e32 v83, v87
	v_mov_b64_e32 v[86:87], v[234:235]
	v_mov_b64_e32 v[88:89], v[236:237]
	v_permlane32_swap_b32_e32 v84, v82
	v_permlane32_swap_b32_e32 v85, v83
	v_lshlrev_b32_e32 v90, 16, v84
	v_and_b32_e32 v91, 0xffff0000, v84
	v_lshlrev_b32_e32 v84, 16, v85
	v_and_b32_e32 v85, 0xffff0000, v85
	s_nop 0
	v_pk_fma_f32 v[64:65], v[64:65], v[86:87], v[90:91]
	v_pk_fma_f32 v[66:67], v[66:67], v[88:89], v[84:85]
	s_cbranch_vccnz .LBB0_896
	v_lshl_add_u64 v[84:85], v[128:129], 2, v[98:99]
	v_lshl_add_u64 v[84:85], v[84:85], 0, v[192:193]
	s_mov_b64 s[36:37], 0
	ds_write_b128 v166, v[64:67] offset:128

.LBB0_898:
	v_mov_b64_e32 v[84:85], v[238:239]
	v_mov_b64_e32 v[86:87], v[240:241]
	v_lshlrev_b32_e32 v88, 16, v82
	v_and_b32_e32 v89, 0xffff0000, v82
	v_lshlrev_b32_e32 v82, 16, v83
	v_and_b32_e32 v83, 0xffff0000, v83
	v_pk_mul_f32 v[68:69], v[68:69], v[96:97]
	v_pk_mul_f32 v[70:71], v[70:71], v[96:97]
	s_mov_b64 s[36:37], -1
	s_and_b64 vcc, exec, s[16:17]
	s_nop 0
	v_pk_fma_f32 v[68:69], v[68:69], v[84:85], v[88:89]
	v_pk_fma_f32 v[70:71], v[70:71], v[86:87], v[82:83]
	s_cbranch_vccnz .LBB0_997
	v_lshl_add_u64 v[82:83], v[128:129], 2, v[98:99]
	v_lshl_add_u64 v[82:83], v[82:83], 0, v[192:193]
	ds_write_b128 v166, v[68:71] offset:160
	s_cbranch_execz .LBB0_998

.LBB0_901:
	s_mov_b64 s[36:37], 0x1dc0040
	v_cvt_pk_bf16_f32 v64, v64, v65
	v_cvt_pk_bf16_f32 v65, v66, v67
	v_cvt_pk_bf16_f32 v66, v68, v69
	v_cvt_pk_bf16_f32 v67, v70, v71
	v_lshl_add_u64 v[80:81], v[80:81], 0, s[36:37]
	v_permlane32_swap_b32_e32 v64, v66
	v_permlane32_swap_b32_e32 v65, v67
	ds_write_b128 v166, v[64:67] offset:64
.LBB0_902:
	v_mov_b32_e32 v133, v193
	v_lshl_add_u64 v[80:81], v[100:101], 0, v[132:133]
	v_add_co_u32_e32 v64, vcc, 0x1dc0000, v80
	v_mov_b64_e32 v[82:83], v[242:243]
	v_mov_b64_e32 v[84:85], v[244:245]
	s_nop 0
	v_addc_co_u32_e32 v65, vcc, 0, v81, vcc
	v_mov_b64_e32 v[64:65], v[198:199]
	v_mov_b64_e32 v[66:67], v[200:201]
	global_load_dwordx4 v[218:221], v[164:165], off
	global_load_dwordx4 v[228:231], v[164:165], off offset:32
	global_load_dwordx4 v[186:189], v[164:165], off offset:64
	global_load_dwordx4 v[198:201], v[164:165], off offset:96
	s_mov_b64 s[36:37], -1
	s_and_b64 vcc, exec, s[16:17]
	s_waitcnt lgkmcnt(0)
	v_mov_b32_e32 v68, v66
	v_mov_b32_e32 v69, v67
	s_nop 0
	v_permlane32_swap_b32_e32 v64, v68
	v_permlane32_swap_b32_e32 v65, v69
	v_lshlrev_b32_e32 v66, 16, v64
	v_and_b32_e32 v67, 0xffff0000, v64
	v_lshlrev_b32_e32 v70, 16, v65
	v_and_b32_e32 v71, 0xffff0000, v65
	v_pk_mul_f32 v[64:65], v[72:73], v[96:97]
	s_nop 0
	v_pk_fma_f32 v[64:65], v[64:65], v[82:83], v[66:67]
	v_pk_mul_f32 v[66:67], v[74:75], v[96:97]
	s_nop 0
	v_pk_fma_f32 v[66:67], v[66:67], v[84:85], v[70:71]
	s_cbranch_vccnz .LBB0_904
	v_lshl_add_u64 v[70:71], v[128:129], 2, v[98:99]
	v_lshl_add_u64 v[70:71], v[70:71], 0, v[192:193]
	s_mov_b64 s[36:37], 0
	ds_write_b128 v166, v[64:67] offset:192

.LBB0_906:
	v_mov_b64_e32 v[70:71], v[246:247]
	v_mov_b64_e32 v[72:73], v[248:249]
	v_lshlrev_b32_e32 v74, 16, v68
	v_and_b32_e32 v75, 0xffff0000, v68
	v_lshlrev_b32_e32 v82, 16, v69
	v_and_b32_e32 v83, 0xffff0000, v69
	v_pk_mul_f32 v[68:69], v[76:77], v[96:97]
	v_pk_mul_f32 v[76:77], v[78:79], v[96:97]
	s_and_b64 vcc, exec, s[16:17]
	s_mov_b64 s[36:37], -1
	s_nop 0
	v_pk_fma_f32 v[68:69], v[68:69], v[70:71], v[74:75]
	v_pk_fma_f32 v[70:71], v[76:77], v[72:73], v[82:83]
	s_cbranch_vccnz .LBB0_999
	v_lshl_add_u64 v[72:73], v[128:129], 2, v[98:99]
	v_lshl_add_u64 v[72:73], v[72:73], 0, v[192:193]
	ds_write_b128 v166, v[68:71] offset:224
	s_cbranch_execz .LBB0_1000

.LBB0_909:
	s_mov_b64 s[36:37], 0x1dc0060
	v_cvt_pk_bf16_f32 v64, v64, v65
	v_cvt_pk_bf16_f32 v65, v66, v67
	v_cvt_pk_bf16_f32 v66, v68, v69
	v_cvt_pk_bf16_f32 v67, v70, v71
	v_lshl_add_u64 v[72:73], v[80:81], 0, s[36:37]
	v_permlane32_swap_b32_e32 v64, v66
	v_permlane32_swap_b32_e32 v65, v67
	ds_write_b128 v166, v[64:67] offset:96
.LBB0_910:
	v_readlane_b32 vcc_lo, v253, 47
	v_readlane_b32 vcc_hi, v253, 48
	s_nop 1
	s_and_b64 vcc, exec, vcc
	s_cbranch_scc0 .Lof1_h
	v_lshrrev_b32_e32 v80, 6, v250
	v_mul_u32_u24_e32 v80, 0x2200, v80
	v_lshrrev_b32_e32 v81, 4, v225
	v_mul_u32_u24_e32 v81, 0x110, v81
	v_and_b32_e32 v82, 15, v225
	v_lshl_add_u32 v81, v82, 4, v81
	v_add_u32_e32 v80, v80, v81
	v_add_u32_e32 v80, 0x1000, v80
	ds_read_b128 v[64:67], v80
	ds_read_b128 v[68:71], v80 offset:1088
	ds_read_b128 v[72:75], v80 offset:2176
	ds_read_b128 v[76:79], v80 offset:3264
	s_waitcnt lgkmcnt(3)
	global_store_dwordx4 v169, v[64:67], s[100:101]
	s_add_u32 s100, s100, 0x4000
	s_addc_u32 s101, s101, 0
	s_waitcnt lgkmcnt(2)
	global_store_dwordx4 v169, v[68:71], s[100:101]
	s_add_u32 s100, s100, 0x4000
	s_addc_u32 s101, s101, 0
	s_waitcnt lgkmcnt(1)
	global_store_dwordx4 v169, v[72:75], s[100:101]
	s_add_u32 s100, s100, 0x4000
	s_addc_u32 s101, s101, 0
	s_waitcnt lgkmcnt(0)
	global_store_dwordx4 v169, v[76:79], s[100:101]
	s_add_u32 s100, s100, 0x4000
	s_addc_u32 s101, s101, 0
	ds_read_b128 v[64:67], v80 offset:4352
	ds_read_b128 v[68:71], v80 offset:5440
	ds_read_b128 v[72:75], v80 offset:6528
	ds_read_b128 v[76:79], v80 offset:7616
	s_waitcnt lgkmcnt(3)
	global_store_dwordx4 v169, v[64:67], s[100:101]
	s_add_u32 s100, s100, 0x4000
	s_addc_u32 s101, s101, 0
	s_waitcnt lgkmcnt(2)
	global_store_dwordx4 v169, v[68:71], s[100:101]
	s_add_u32 s100, s100, 0x4000
	s_addc_u32 s101, s101, 0
	s_waitcnt lgkmcnt(1)
	global_store_dwordx4 v169, v[72:75], s[100:101]
	s_add_u32 s100, s100, 0x4000
	s_addc_u32 s101, s101, 0
	s_waitcnt lgkmcnt(0)
	global_store_dwordx4 v169, v[76:79], s[100:101]
	s_add_u32 s100, s100, 0x4000
	s_addc_u32 s101, s101, 0
	s_branch .Lof1_d
.Lof1_h:
	v_lshrrev_b32_e32 v80, 6, v250
	v_mul_u32_u24_e32 v80, 0x1200, v80
	v_lshrrev_b32_e32 v81, 3, v225
	v_mul_u32_u24_e32 v81, 0x90, v81
	v_and_b32_e32 v82, 7, v225
	v_lshl_add_u32 v81, v82, 4, v81
	v_add_u32_e32 v80, v80, v81
	v_add_u32_e32 v80, 0x1000, v80
	ds_read_b128 v[64:67], v80
	ds_read_b128 v[68:71], v80 offset:1152
	ds_read_b128 v[72:75], v80 offset:2304
	ds_read_b128 v[76:79], v80 offset:3456
	s_waitcnt lgkmcnt(3)
	global_store_dwordx4 v169, v[64:67], s[100:101]
	s_add_u32 s100, s100, 0x4000
	s_addc_u32 s101, s101, 0
	s_waitcnt lgkmcnt(2)
	global_store_dwordx4 v169, v[68:71], s[100:101]
	s_add_u32 s100, s100, 0x4000
	s_addc_u32 s101, s101, 0
	s_waitcnt lgkmcnt(1)
	global_store_dwordx4 v169, v[72:75], s[100:101]
	s_add_u32 s100, s100, 0x4000
	s_addc_u32 s101, s101, 0
	s_waitcnt lgkmcnt(0)
	global_store_dwordx4 v169, v[76:79], s[100:101]
	s_add_u32 s100, s100, 0x4000
	s_addc_u32 s101, s101, 0
.Lof1_d:
	s_nop 1
	v_lshlrev_b64 v[66:67], 11, v[136:137]
	v_lshl_add_u64 v[66:67], s[26:27], 0, v[66:67]
	v_lshl_add_u64 v[66:67], v[128:129], 1, v[66:67]
	v_mov_b32_e32 v133, v193
	v_lshl_add_u64 v[70:71], v[66:67], 0, v[132:133]
	s_waitcnt vmcnt(6)
	v_mov_b64_e32 v[76:77], v[170:171]
	v_mov_b64_e32 v[78:79], v[172:173]
	ds_read_b32 v64, v154 offset:2304
	v_readlane_b32 s40, v252, 2
	v_lshlrev_b64 v[68:69], 10, v[136:137]
	v_readlane_b32 s41, v252, 3
	s_mov_b64 s[36:37], -1
	s_waitcnt lgkmcnt(0)
	v_fmamk_f32 v64, v64, 0x3a800000, v224
	v_cmp_gt_f32_e32 vcc, s31, v64
	v_mul_f32_e32 v65, 0x4b800000, v64
	v_readlane_b32 s42, v252, 4
	v_cndmask_b32_e32 v64, v64, v65, vcc
	v_rsq_f32_e32 v64, v64
	v_readlane_b32 s43, v252, 5
	v_readlane_b32 s44, v252, 6
	v_readlane_b32 s45, v252, 7
	v_mul_f32_e32 v65, 0x45800000, v64
	v_cndmask_b32_e32 v64, v64, v65, vcc
	v_pk_mul_f32 v[48:49], v[48:49], v[64:65] op_sel_hi:[1,0]
	v_pk_mul_f32 v[50:51], v[50:51], v[64:65] op_sel_hi:[1,0]
	s_and_b64 vcc, exec, s[16:17]
	v_readlane_b32 s46, v252, 8
	v_readlane_b32 s47, v252, 9
	s_nop 0
	v_mov_b32_e32 v73, v78
	v_mov_b32_e32 v74, v79
	v_mov_b64_e32 v[78:79], v[202:203]
	v_mov_b64_e32 v[80:81], v[204:205]
	v_permlane32_swap_b32_e32 v76, v73
	v_permlane32_swap_b32_e32 v77, v74
	v_lshlrev_b32_e32 v66, 16, v76
	v_and_b32_e32 v67, 0xffff0000, v76
	v_lshlrev_b32_e32 v76, 16, v77
	v_and_b32_e32 v77, 0xffff0000, v77
	s_nop 0
	v_pk_fma_f32 v[48:49], v[78:79], v[48:49], v[66:67]
	v_pk_fma_f32 v[50:51], v[80:81], v[50:51], v[76:77]
	v_lshl_add_u64 v[66:67], v[68:69], 2, s[40:41]
	s_cbranch_vccnz .LBB0_912
	v_lshl_add_u64 v[76:77], v[128:129], 2, v[66:67]
	v_lshl_add_u64 v[76:77], v[76:77], 0, v[192:193]
	s_mov_b64 s[36:37], 0
	ds_write_b128 v166, v[48:51]

.LBB0_914:
	v_mov_b64_e32 v[76:77], v[206:207]
	v_mov_b64_e32 v[78:79], v[208:209]
	v_mov_b32_e32 v65, v64
	v_lshlrev_b32_e32 v80, 16, v73
	v_and_b32_e32 v81, 0xffff0000, v73
	v_lshlrev_b32_e32 v82, 16, v74
	v_and_b32_e32 v83, 0xffff0000, v74
	v_pk_mul_f32 v[52:53], v[52:53], v[64:65]
	v_pk_mul_f32 v[54:55], v[54:55], v[64:65]
	s_mov_b64 s[36:37], -1
	s_and_b64 vcc, exec, s[16:17]
	s_nop 0
	v_pk_fma_f32 v[52:53], v[52:53], v[76:77], v[80:81]
	v_pk_fma_f32 v[54:55], v[54:55], v[78:79], v[82:83]
	s_cbranch_vccnz .LBB0_1001
	v_lshl_add_u64 v[74:75], v[128:129], 2, v[66:67]
	v_lshl_add_u64 v[74:75], v[74:75], 0, v[192:193]
	ds_write_b128 v166, v[52:55] offset:32
	s_cbranch_execz .LBB0_1002

.LBB0_917:
	v_cvt_pk_bf16_f32 v48, v48, v49
	v_cvt_pk_bf16_f32 v49, v50, v51
	v_cvt_pk_bf16_f32 v50, v52, v53
	v_cvt_pk_bf16_f32 v51, v54, v55
	s_nop 0
	v_permlane32_swap_b32_e32 v48, v50
	v_permlane32_swap_b32_e32 v49, v51
	ds_write_b128 v166, v[48:51]
.LBB0_918:
	s_nop 1
	v_lshl_add_u64 v[48:49], v[68:69], 1, s[0:1]
	v_lshl_add_u64 v[68:69], v[128:129], 1, v[48:49]
	v_mov_b32_e32 v133, v193
	v_lshl_add_u64 v[70:71], v[68:69], 0, v[132:133]
	v_add_co_u32_e32 v48, vcc, 0x1dc0000, v70
	v_mov_b64_e32 v[74:75], v[210:211]
	v_mov_b64_e32 v[76:77], v[212:213]
	s_nop 0
	v_addc_co_u32_e32 v49, vcc, 0, v71, vcc
	v_mov_b64_e32 v[48:49], v[174:175]
	v_mov_b64_e32 v[50:51], v[176:177]
	s_mov_b64 s[36:37], -1
	s_and_b64 vcc, exec, s[16:17]
	s_waitcnt lgkmcnt(0)
	v_mov_b32_e32 v52, v50
	v_mov_b32_e32 v53, v51
	s_nop 0
	v_permlane32_swap_b32_e32 v48, v52
	v_permlane32_swap_b32_e32 v49, v53
	v_lshlrev_b32_e32 v50, 16, v48
	v_and_b32_e32 v51, 0xffff0000, v48
	v_lshlrev_b32_e32 v54, 16, v49
	v_and_b32_e32 v55, 0xffff0000, v49
	v_pk_mul_f32 v[48:49], v[56:57], v[64:65]
	s_nop 0
	v_pk_fma_f32 v[48:49], v[48:49], v[74:75], v[50:51]
	v_pk_mul_f32 v[50:51], v[58:59], v[64:65]
	s_nop 0
	v_pk_fma_f32 v[50:51], v[50:51], v[76:77], v[54:55]
	s_cbranch_vccnz .LBB0_920
	v_lshl_add_u64 v[54:55], v[128:129], 2, v[66:67]
	v_lshl_add_u64 v[54:55], v[54:55], 0, v[192:193]
	s_mov_b64 s[36:37], 0
	ds_write_b128 v166, v[48:51] offset:64

.LBB0_922:
	v_mov_b64_e32 v[54:55], v[214:215]
	v_mov_b64_e32 v[56:57], v[216:217]
	v_lshlrev_b32_e32 v58, 16, v52
	v_and_b32_e32 v59, 0xffff0000, v52
	v_lshlrev_b32_e32 v74, 16, v53
	v_and_b32_e32 v75, 0xffff0000, v53
	v_pk_mul_f32 v[52:53], v[60:61], v[64:65]
	v_pk_mul_f32 v[60:61], v[62:63], v[64:65]
	s_and_b64 vcc, exec, s[16:17]
	s_mov_b64 s[36:37], -1
	s_nop 0
	v_pk_fma_f32 v[52:53], v[52:53], v[54:55], v[58:59]
	v_pk_fma_f32 v[54:55], v[60:61], v[56:57], v[74:75]
	s_cbranch_vccnz .LBB0_1003
	v_lshl_add_u64 v[56:57], v[128:129], 2, v[66:67]
	v_lshl_add_u64 v[56:57], v[56:57], 0, v[192:193]
	ds_write_b128 v166, v[52:55] offset:96
	s_cbranch_execz .LBB0_1004

.LBB0_925:
	s_mov_b64 s[36:37], 0x1dc0020
	v_cvt_pk_bf16_f32 v48, v48, v49
	v_cvt_pk_bf16_f32 v49, v50, v51
	v_cvt_pk_bf16_f32 v50, v52, v53
	v_cvt_pk_bf16_f32 v51, v54, v55
	v_lshl_add_u64 v[56:57], v[70:71], 0, s[36:37]
	v_permlane32_swap_b32_e32 v48, v50
	v_permlane32_swap_b32_e32 v49, v51
	ds_write_b128 v166, v[48:51] offset:32
.LBB0_926:
	v_mov_b32_e32 v133, v193
	s_nop 0
	v_lshl_add_u64 v[48:49], v[68:69], 0, v[132:133]
	v_add_co_u32_e32 v50, vcc, 0x1dc0000, v48
	v_pk_mul_f32 v[32:33], v[32:33], v[64:65]
	s_nop 0
	v_addc_co_u32_e32 v51, vcc, 0, v49, vcc
	v_mov_b64_e32 v[52:53], v[178:179]
	v_mov_b64_e32 v[54:55], v[180:181]
	v_pk_mul_f32 v[34:35], v[34:35], v[64:65]
	s_mov_b64 s[36:37], -1
	s_and_b64 vcc, exec, s[16:17]
	s_waitcnt lgkmcnt(0)
	v_mov_b32_e32 v50, v54
	v_mov_b32_e32 v51, v55
	v_mov_b64_e32 v[54:55], v[234:235]
	v_mov_b64_e32 v[56:57], v[236:237]
	v_permlane32_swap_b32_e32 v52, v50
	v_permlane32_swap_b32_e32 v53, v51
	v_lshlrev_b32_e32 v58, 16, v52
	v_and_b32_e32 v59, 0xffff0000, v52
	v_lshlrev_b32_e32 v52, 16, v53
	v_and_b32_e32 v53, 0xffff0000, v53
	s_nop 0
	v_pk_fma_f32 v[32:33], v[32:33], v[54:55], v[58:59]
	v_pk_fma_f32 v[34:35], v[34:35], v[56:57], v[52:53]
	s_cbranch_vccnz .LBB0_928
	v_lshl_add_u64 v[52:53], v[128:129], 2, v[66:67]
	v_lshl_add_u64 v[52:53], v[52:53], 0, v[192:193]
	s_mov_b64 s[36:37], 0
	ds_write_b128 v166, v[32:35] offset:128

.LBB0_930:
	v_mov_b64_e32 v[52:53], v[238:239]
	v_mov_b64_e32 v[54:55], v[240:241]
	v_lshlrev_b32_e32 v56, 16, v50
	v_and_b32_e32 v57, 0xffff0000, v50
	v_lshlrev_b32_e32 v50, 16, v51
	v_and_b32_e32 v51, 0xffff0000, v51
	v_pk_mul_f32 v[36:37], v[36:37], v[64:65]
	v_pk_mul_f32 v[38:39], v[38:39], v[64:65]
	s_mov_b64 s[36:37], -1
	s_and_b64 vcc, exec, s[16:17]
	s_nop 0
	v_pk_fma_f32 v[36:37], v[36:37], v[52:53], v[56:57]
	v_pk_fma_f32 v[38:39], v[38:39], v[54:55], v[50:51]
	s_cbranch_vccnz .LBB0_1005
	v_lshl_add_u64 v[50:51], v[128:129], 2, v[66:67]
	v_lshl_add_u64 v[50:51], v[50:51], 0, v[192:193]
	ds_write_b128 v166, v[36:39] offset:160
	s_cbranch_execz .LBB0_1006

.LBB0_933:
	s_mov_b64 s[36:37], 0x1dc0040
	v_cvt_pk_bf16_f32 v32, v32, v33
	v_cvt_pk_bf16_f32 v33, v34, v35
	v_cvt_pk_bf16_f32 v34, v36, v37
	v_cvt_pk_bf16_f32 v35, v38, v39
	v_lshl_add_u64 v[48:49], v[48:49], 0, s[36:37]
	v_permlane32_swap_b32_e32 v32, v34
	v_permlane32_swap_b32_e32 v33, v35
	ds_write_b128 v166, v[32:35] offset:64
.LBB0_934:
	v_mov_b32_e32 v133, v193
	v_lshl_add_u64 v[48:49], v[68:69], 0, v[132:133]
	v_add_co_u32_e32 v32, vcc, 0x1dc0000, v48
	v_mov_b64_e32 v[50:51], v[242:243]
	v_mov_b64_e32 v[52:53], v[244:245]
	s_nop 0
	v_addc_co_u32_e32 v33, vcc, 0, v49, vcc
	v_mov_b64_e32 v[32:33], v[182:183]
	v_mov_b64_e32 v[34:35], v[184:185]
	s_mov_b64 s[36:37], -1
	s_and_b64 vcc, exec, s[16:17]
	s_waitcnt lgkmcnt(0)
	v_mov_b32_e32 v36, v34
	v_mov_b32_e32 v37, v35
	s_nop 0
	v_permlane32_swap_b32_e32 v32, v36
	v_permlane32_swap_b32_e32 v33, v37
	v_lshlrev_b32_e32 v34, 16, v32
	v_and_b32_e32 v35, 0xffff0000, v32
	v_lshlrev_b32_e32 v38, 16, v33
	v_and_b32_e32 v39, 0xffff0000, v33
	v_pk_mul_f32 v[32:33], v[40:41], v[64:65]
	s_nop 0
	v_pk_fma_f32 v[32:33], v[32:33], v[50:51], v[34:35]
	v_pk_mul_f32 v[34:35], v[42:43], v[64:65]
	s_nop 0
	v_pk_fma_f32 v[34:35], v[34:35], v[52:53], v[38:39]
	s_cbranch_vccnz .LBB0_936
	v_lshl_add_u64 v[38:39], v[128:129], 2, v[66:67]
	v_lshl_add_u64 v[38:39], v[38:39], 0, v[192:193]
	s_mov_b64 s[36:37], 0
	ds_write_b128 v166, v[32:35] offset:192

.LBB0_938:
	v_mov_b64_e32 v[38:39], v[246:247]
	v_mov_b64_e32 v[40:41], v[248:249]
	v_lshlrev_b32_e32 v42, 16, v36
	v_and_b32_e32 v43, 0xffff0000, v36
	v_lshlrev_b32_e32 v50, 16, v37
	v_and_b32_e32 v51, 0xffff0000, v37
	v_pk_mul_f32 v[36:37], v[44:45], v[64:65]
	v_pk_mul_f32 v[44:45], v[46:47], v[64:65]
	s_and_b64 vcc, exec, s[16:17]
	s_mov_b64 s[36:37], -1
	s_nop 0
	v_pk_fma_f32 v[36:37], v[36:37], v[38:39], v[42:43]
	v_pk_fma_f32 v[38:39], v[44:45], v[40:41], v[50:51]
	s_cbranch_vccnz .LBB0_1007
	v_lshl_add_u64 v[40:41], v[128:129], 2, v[66:67]
	v_lshl_add_u64 v[40:41], v[40:41], 0, v[192:193]
	ds_write_b128 v166, v[36:39] offset:224
	s_cbranch_execz .LBB0_1008

.LBB0_941:
	s_mov_b64 s[36:37], 0x1dc0060
	v_cvt_pk_bf16_f32 v32, v32, v33
	v_cvt_pk_bf16_f32 v33, v34, v35
	v_cvt_pk_bf16_f32 v34, v36, v37
	v_cvt_pk_bf16_f32 v35, v38, v39
	v_lshl_add_u64 v[40:41], v[48:49], 0, s[36:37]
	v_permlane32_swap_b32_e32 v32, v34
	v_permlane32_swap_b32_e32 v33, v35
	ds_write_b128 v166, v[32:35] offset:96
.LBB0_942:
	v_readlane_b32 vcc_lo, v253, 47
	v_readlane_b32 vcc_hi, v253, 48
	s_nop 1
	s_and_b64 vcc, exec, vcc
	s_cbranch_scc0 .Lof2_h
	v_lshrrev_b32_e32 v48, 6, v250
	v_mul_u32_u24_e32 v48, 0x2200, v48
	v_lshrrev_b32_e32 v49, 4, v225
	v_mul_u32_u24_e32 v49, 0x110, v49
	v_and_b32_e32 v50, 15, v225
	v_lshl_add_u32 v49, v50, 4, v49
	v_add_u32_e32 v48, v48, v49
	v_add_u32_e32 v48, 0x1000, v48
	ds_read_b128 v[32:35], v48
	ds_read_b128 v[36:39], v48 offset:1088
	ds_read_b128 v[40:43], v48 offset:2176
	ds_read_b128 v[44:47], v48 offset:3264
	s_waitcnt lgkmcnt(3)
	global_store_dwordx4 v169, v[32:35], s[100:101]
	s_add_u32 s100, s100, 0x4000
	s_addc_u32 s101, s101, 0
	s_waitcnt lgkmcnt(2)
	global_store_dwordx4 v169, v[36:39], s[100:101]
	s_add_u32 s100, s100, 0x4000
	s_addc_u32 s101, s101, 0
	s_waitcnt lgkmcnt(1)
	global_store_dwordx4 v169, v[40:43], s[100:101]
	s_add_u32 s100, s100, 0x4000
	s_addc_u32 s101, s101, 0
	s_waitcnt lgkmcnt(0)
	global_store_dwordx4 v169, v[44:47], s[100:101]
	s_add_u32 s100, s100, 0x4000
	s_addc_u32 s101, s101, 0
	ds_read_b128 v[32:35], v48 offset:4352
	ds_read_b128 v[36:39], v48 offset:5440
	ds_read_b128 v[40:43], v48 offset:6528
	ds_read_b128 v[44:47], v48 offset:7616
	s_waitcnt lgkmcnt(3)
	global_store_dwordx4 v169, v[32:35], s[100:101]
	s_add_u32 s100, s100, 0x4000
	s_addc_u32 s101, s101, 0
	s_waitcnt lgkmcnt(2)
	global_store_dwordx4 v169, v[36:39], s[100:101]
	s_add_u32 s100, s100, 0x4000
	s_addc_u32 s101, s101, 0
	s_waitcnt lgkmcnt(1)
	global_store_dwordx4 v169, v[40:43], s[100:101]
	s_add_u32 s100, s100, 0x4000
	s_addc_u32 s101, s101, 0
	s_waitcnt lgkmcnt(0)
	global_store_dwordx4 v169, v[44:47], s[100:101]
	s_add_u32 s100, s100, 0x4000
	s_addc_u32 s101, s101, 0
	s_branch .Lof2_d
.Lof2_h:
	v_lshrrev_b32_e32 v48, 6, v250
	v_mul_u32_u24_e32 v48, 0x1200, v48
	v_lshrrev_b32_e32 v49, 3, v225
	v_mul_u32_u24_e32 v49, 0x90, v49
	v_and_b32_e32 v50, 7, v225
	v_lshl_add_u32 v49, v50, 4, v49
	v_add_u32_e32 v48, v48, v49
	v_add_u32_e32 v48, 0x1000, v48
	ds_read_b128 v[32:35], v48
	ds_read_b128 v[36:39], v48 offset:1152
	ds_read_b128 v[40:43], v48 offset:2304
	ds_read_b128 v[44:47], v48 offset:3456
	s_waitcnt lgkmcnt(3)
	global_store_dwordx4 v169, v[32:35], s[100:101]
	s_add_u32 s100, s100, 0x4000
	s_addc_u32 s101, s101, 0
	s_waitcnt lgkmcnt(2)
	global_store_dwordx4 v169, v[36:39], s[100:101]
	s_add_u32 s100, s100, 0x4000
	s_addc_u32 s101, s101, 0
	s_waitcnt lgkmcnt(1)
	global_store_dwordx4 v169, v[40:43], s[100:101]
	s_add_u32 s100, s100, 0x4000
	s_addc_u32 s101, s101, 0
	s_waitcnt lgkmcnt(0)
	global_store_dwordx4 v169, v[44:47], s[100:101]
	s_add_u32 s100, s100, 0x4000
	s_addc_u32 s101, s101, 0
.Lof2_d:
	s_nop 1
	v_lshlrev_b64 v[34:35], 11, v[134:135]
	v_lshl_add_u64 v[34:35], s[26:27], 0, v[34:35]
	v_lshl_add_u64 v[34:35], v[128:129], 1, v[34:35]
	v_mov_b32_e32 v133, v193
	v_lshl_add_u64 v[38:39], v[34:35], 0, v[132:133]
	s_waitcnt vmcnt(4)
	v_mov_b64_e32 v[44:45], v[218:219]
	v_mov_b64_e32 v[46:47], v[220:221]
	ds_read_b32 v32, v154 offset:2432
	v_readlane_b32 s40, v252, 2
	v_lshlrev_b64 v[36:37], 10, v[134:135]
	v_readlane_b32 s41, v252, 3
	s_mov_b64 s[36:37], -1
	s_waitcnt lgkmcnt(0)
	v_fmamk_f32 v32, v32, 0x3a800000, v224
	v_cmp_gt_f32_e32 vcc, s31, v32
	v_mul_f32_e32 v33, 0x4b800000, v32
	v_readlane_b32 s42, v252, 4
	v_cndmask_b32_e32 v32, v32, v33, vcc
	v_rsq_f32_e32 v32, v32
	v_readlane_b32 s43, v252, 5
	v_readlane_b32 s44, v252, 6
	v_readlane_b32 s45, v252, 7
	v_mul_f32_e32 v33, 0x45800000, v32
	v_cndmask_b32_e32 v32, v32, v33, vcc
	v_pk_mul_f32 v[16:17], v[16:17], v[32:33] op_sel_hi:[1,0]
	v_pk_mul_f32 v[18:19], v[18:19], v[32:33] op_sel_hi:[1,0]
	s_and_b64 vcc, exec, s[16:17]
	v_readlane_b32 s46, v252, 8
	v_readlane_b32 s47, v252, 9
	s_nop 0
	v_mov_b32_e32 v41, v46
	v_mov_b32_e32 v42, v47
	v_mov_b64_e32 v[46:47], v[202:203]
	v_mov_b64_e32 v[48:49], v[204:205]
	v_permlane32_swap_b32_e32 v44, v41
	v_permlane32_swap_b32_e32 v45, v42
	v_lshlrev_b32_e32 v34, 16, v44
	v_and_b32_e32 v35, 0xffff0000, v44
	v_lshlrev_b32_e32 v44, 16, v45
	v_and_b32_e32 v45, 0xffff0000, v45
	s_nop 0
	v_pk_fma_f32 v[16:17], v[46:47], v[16:17], v[34:35]
	v_pk_fma_f32 v[18:19], v[48:49], v[18:19], v[44:45]
	v_lshl_add_u64 v[34:35], v[36:37], 2, s[40:41]
	s_cbranch_vccnz .LBB0_944
	v_lshl_add_u64 v[44:45], v[128:129], 2, v[34:35]
	v_lshl_add_u64 v[44:45], v[44:45], 0, v[192:193]
	s_mov_b64 s[36:37], 0
	ds_write_b128 v166, v[16:19]

.LBB0_946:
	v_mov_b64_e32 v[44:45], v[206:207]
	v_mov_b64_e32 v[46:47], v[208:209]
	v_mov_b32_e32 v33, v32
	v_lshlrev_b32_e32 v48, 16, v41
	v_and_b32_e32 v49, 0xffff0000, v41
	v_lshlrev_b32_e32 v50, 16, v42
	v_and_b32_e32 v51, 0xffff0000, v42
	v_pk_mul_f32 v[20:21], v[20:21], v[32:33]
	v_pk_mul_f32 v[22:23], v[22:23], v[32:33]
	s_mov_b64 s[36:37], -1
	s_and_b64 vcc, exec, s[16:17]
	s_nop 0
	v_pk_fma_f32 v[20:21], v[20:21], v[44:45], v[48:49]
	v_pk_fma_f32 v[22:23], v[22:23], v[46:47], v[50:51]
	s_cbranch_vccnz .LBB0_1009
	v_lshl_add_u64 v[42:43], v[128:129], 2, v[34:35]
	v_lshl_add_u64 v[42:43], v[42:43], 0, v[192:193]
	ds_write_b128 v166, v[20:23] offset:32
	s_cbranch_execz .LBB0_1010

.LBB0_949:
	v_cvt_pk_bf16_f32 v16, v16, v17
	v_cvt_pk_bf16_f32 v17, v18, v19
	v_cvt_pk_bf16_f32 v18, v20, v21
	v_cvt_pk_bf16_f32 v19, v22, v23
	s_nop 0
	v_permlane32_swap_b32_e32 v16, v18
	v_permlane32_swap_b32_e32 v17, v19
	ds_write_b128 v166, v[16:19]
.LBB0_950:
	s_nop 1
	v_lshl_add_u64 v[16:17], v[36:37], 1, s[0:1]
	v_lshl_add_u64 v[36:37], v[128:129], 1, v[16:17]
	v_mov_b32_e32 v133, v193
	v_lshl_add_u64 v[38:39], v[36:37], 0, v[132:133]
	v_add_co_u32_e32 v16, vcc, 0x1dc0000, v38
	v_mov_b64_e32 v[42:43], v[210:211]
	v_mov_b64_e32 v[44:45], v[212:213]
	s_nop 0
	v_addc_co_u32_e32 v17, vcc, 0, v39, vcc
	v_mov_b64_e32 v[16:17], v[228:229]
	v_mov_b64_e32 v[18:19], v[230:231]
	s_mov_b64 s[36:37], -1
	s_and_b64 vcc, exec, s[16:17]
	s_waitcnt lgkmcnt(0)
	v_mov_b32_e32 v20, v18
	v_mov_b32_e32 v21, v19
	s_nop 0
	v_permlane32_swap_b32_e32 v16, v20
	v_permlane32_swap_b32_e32 v17, v21
	v_lshlrev_b32_e32 v18, 16, v16
	v_and_b32_e32 v19, 0xffff0000, v16
	v_lshlrev_b32_e32 v22, 16, v17
	v_and_b32_e32 v23, 0xffff0000, v17
	v_pk_mul_f32 v[16:17], v[24:25], v[32:33]
	s_nop 0
	v_pk_fma_f32 v[16:17], v[16:17], v[42:43], v[18:19]
	v_pk_mul_f32 v[18:19], v[26:27], v[32:33]
	s_nop 0
	v_pk_fma_f32 v[18:19], v[18:19], v[44:45], v[22:23]
	s_cbranch_vccnz .LBB0_952
	v_lshl_add_u64 v[22:23], v[128:129], 2, v[34:35]
	v_lshl_add_u64 v[22:23], v[22:23], 0, v[192:193]
	s_mov_b64 s[36:37], 0
	ds_write_b128 v166, v[16:19] offset:64

.LBB0_954:
	v_mov_b64_e32 v[22:23], v[214:215]
	v_mov_b64_e32 v[24:25], v[216:217]
	v_lshlrev_b32_e32 v26, 16, v20
	v_and_b32_e32 v27, 0xffff0000, v20
	v_lshlrev_b32_e32 v42, 16, v21
	v_and_b32_e32 v43, 0xffff0000, v21
	v_pk_mul_f32 v[20:21], v[28:29], v[32:33]
	v_pk_mul_f32 v[28:29], v[30:31], v[32:33]
	s_and_b64 vcc, exec, s[16:17]
	s_mov_b64 s[36:37], -1
	s_nop 0
	v_pk_fma_f32 v[20:21], v[20:21], v[22:23], v[26:27]
	v_pk_fma_f32 v[22:23], v[28:29], v[24:25], v[42:43]
	s_cbranch_vccnz .LBB0_1011
	v_lshl_add_u64 v[24:25], v[128:129], 2, v[34:35]
	v_lshl_add_u64 v[24:25], v[24:25], 0, v[192:193]
	ds_write_b128 v166, v[20:23] offset:96
	s_cbranch_execz .LBB0_1012

.LBB0_957:
	s_mov_b64 s[36:37], 0x1dc0020
	v_cvt_pk_bf16_f32 v16, v16, v17
	v_cvt_pk_bf16_f32 v17, v18, v19
	v_cvt_pk_bf16_f32 v18, v20, v21
	v_cvt_pk_bf16_f32 v19, v22, v23
	v_lshl_add_u64 v[24:25], v[38:39], 0, s[36:37]
	v_permlane32_swap_b32_e32 v16, v18
	v_permlane32_swap_b32_e32 v17, v19
	ds_write_b128 v166, v[16:19] offset:32
.LBB0_958:
	v_mov_b32_e32 v133, v193
	s_nop 0
	v_lshl_add_u64 v[16:17], v[36:37], 0, v[132:133]
	v_add_co_u32_e32 v18, vcc, 0x1dc0000, v16
	v_pk_mul_f32 v[0:1], v[0:1], v[32:33]
	s_nop 0
	v_addc_co_u32_e32 v19, vcc, 0, v17, vcc
	v_mov_b64_e32 v[20:21], v[186:187]
	v_mov_b64_e32 v[22:23], v[188:189]
	v_pk_mul_f32 v[2:3], v[2:3], v[32:33]
	s_mov_b64 s[36:37], -1
	s_and_b64 vcc, exec, s[16:17]
	s_waitcnt lgkmcnt(0)
	v_mov_b32_e32 v18, v22
	v_mov_b32_e32 v19, v23
	v_mov_b64_e32 v[22:23], v[234:235]
	v_mov_b64_e32 v[24:25], v[236:237]
	v_permlane32_swap_b32_e32 v20, v18
	v_permlane32_swap_b32_e32 v21, v19
	v_lshlrev_b32_e32 v26, 16, v20
	v_and_b32_e32 v27, 0xffff0000, v20
	v_lshlrev_b32_e32 v20, 16, v21
	v_and_b32_e32 v21, 0xffff0000, v21
	s_nop 0
	v_pk_fma_f32 v[0:1], v[0:1], v[22:23], v[26:27]
	v_pk_fma_f32 v[2:3], v[2:3], v[24:25], v[20:21]
	s_cbranch_vccnz .LBB0_960
	v_lshl_add_u64 v[20:21], v[128:129], 2, v[34:35]
	v_lshl_add_u64 v[20:21], v[20:21], 0, v[192:193]
	s_mov_b64 s[36:37], 0
	ds_write_b128 v166, v[0:3] offset:128

.LBB0_962:
	v_mov_b64_e32 v[20:21], v[238:239]
	v_mov_b64_e32 v[22:23], v[240:241]
	v_lshlrev_b32_e32 v24, 16, v18
	v_and_b32_e32 v25, 0xffff0000, v18
	v_lshlrev_b32_e32 v18, 16, v19
	v_and_b32_e32 v19, 0xffff0000, v19
	v_pk_mul_f32 v[4:5], v[4:5], v[32:33]
	v_pk_mul_f32 v[6:7], v[6:7], v[32:33]
	s_mov_b64 s[36:37], -1
	s_and_b64 vcc, exec, s[16:17]
	s_nop 0
	v_pk_fma_f32 v[4:5], v[4:5], v[20:21], v[24:25]
	v_pk_fma_f32 v[6:7], v[6:7], v[22:23], v[18:19]
	s_cbranch_vccnz .LBB0_1013
	v_lshl_add_u64 v[18:19], v[128:129], 2, v[34:35]
	v_lshl_add_u64 v[18:19], v[18:19], 0, v[192:193]
	ds_write_b128 v166, v[4:7] offset:160
	s_cbranch_execz .LBB0_1014

.LBB0_965:
	s_mov_b64 s[36:37], 0x1dc0040
	v_cvt_pk_bf16_f32 v0, v0, v1
	v_cvt_pk_bf16_f32 v1, v2, v3
	v_cvt_pk_bf16_f32 v2, v4, v5
	v_cvt_pk_bf16_f32 v3, v6, v7
	v_lshl_add_u64 v[16:17], v[16:17], 0, s[36:37]
	v_permlane32_swap_b32_e32 v0, v2
	v_permlane32_swap_b32_e32 v1, v3
	ds_write_b128 v166, v[0:3] offset:64
.LBB0_966:
	v_mov_b32_e32 v133, v193
	v_lshl_add_u64 v[16:17], v[36:37], 0, v[132:133]
	v_add_co_u32_e32 v0, vcc, 0x1dc0000, v16
	v_mov_b64_e32 v[18:19], v[242:243]
	v_mov_b64_e32 v[20:21], v[244:245]
	s_nop 0
	v_addc_co_u32_e32 v1, vcc, 0, v17, vcc
	v_mov_b64_e32 v[0:1], v[198:199]
	v_mov_b64_e32 v[2:3], v[200:201]
	s_mov_b64 s[36:37], -1
	s_and_b64 vcc, exec, s[16:17]
	s_waitcnt lgkmcnt(0)
	v_mov_b32_e32 v4, v2
	v_mov_b32_e32 v5, v3
	s_nop 0
	v_permlane32_swap_b32_e32 v0, v4
	v_permlane32_swap_b32_e32 v1, v5
	v_lshlrev_b32_e32 v2, 16, v0
	v_and_b32_e32 v3, 0xffff0000, v0
	v_lshlrev_b32_e32 v6, 16, v1
	v_and_b32_e32 v7, 0xffff0000, v1
	v_pk_mul_f32 v[0:1], v[8:9], v[32:33]
	s_nop 0
	v_pk_fma_f32 v[0:1], v[0:1], v[18:19], v[2:3]
	v_pk_mul_f32 v[2:3], v[10:11], v[32:33]
	s_nop 0
	v_pk_fma_f32 v[2:3], v[2:3], v[20:21], v[6:7]
	s_cbranch_vccnz .LBB0_968
	v_lshl_add_u64 v[6:7], v[128:129], 2, v[34:35]
	v_lshl_add_u64 v[6:7], v[6:7], 0, v[192:193]
	s_mov_b64 s[36:37], 0
	ds_write_b128 v166, v[0:3] offset:192

.LBB0_970:
	v_mov_b64_e32 v[6:7], v[246:247]
	v_mov_b64_e32 v[8:9], v[248:249]
	v_lshlrev_b32_e32 v10, 16, v4
	v_and_b32_e32 v11, 0xffff0000, v4
	v_lshlrev_b32_e32 v18, 16, v5
	v_and_b32_e32 v19, 0xffff0000, v5
	v_pk_mul_f32 v[4:5], v[12:13], v[32:33]
	v_pk_mul_f32 v[12:13], v[14:15], v[32:33]
	s_and_b64 vcc, exec, s[16:17]
	s_mov_b64 s[16:17], -1
	s_nop 0
	v_pk_fma_f32 v[4:5], v[4:5], v[6:7], v[10:11]
	v_pk_fma_f32 v[6:7], v[12:13], v[8:9], v[18:19]
	s_cbranch_vccnz .LBB0_1015
	v_lshl_add_u64 v[8:9], v[128:129], 2, v[34:35]
	v_lshl_add_u64 v[8:9], v[8:9], 0, v[192:193]
	ds_write_b128 v166, v[4:7] offset:224
	s_cbranch_execz .LBB0_1016

.LBB0_973:
	s_mov_b64 s[16:17], 0x1dc0060
	v_cvt_pk_bf16_f32 v0, v0, v1
	v_cvt_pk_bf16_f32 v1, v2, v3
	v_cvt_pk_bf16_f32 v2, v4, v5
	v_cvt_pk_bf16_f32 v3, v6, v7
	v_lshl_add_u64 v[8:9], v[16:17], 0, s[16:17]
	v_permlane32_swap_b32_e32 v0, v2
	v_permlane32_swap_b32_e32 v1, v3
	ds_write_b128 v166, v[0:3] offset:96
.LBB0_974:
	v_readlane_b32 vcc_lo, v253, 47
	v_readlane_b32 vcc_hi, v253, 48
	s_nop 1
	s_and_b64 vcc, exec, vcc
	s_cbranch_scc0 .Lof3_h
	v_lshrrev_b32_e32 v16, 6, v250
	v_mul_u32_u24_e32 v16, 0x2200, v16
	v_lshrrev_b32_e32 v17, 4, v225
	v_mul_u32_u24_e32 v17, 0x110, v17
	v_and_b32_e32 v18, 15, v225
	v_lshl_add_u32 v17, v18, 4, v17
	v_add_u32_e32 v16, v16, v17
	v_add_u32_e32 v16, 0x1000, v16
	ds_read_b128 v[0:3], v16
	ds_read_b128 v[4:7], v16 offset:1088
	ds_read_b128 v[8:11], v16 offset:2176
	ds_read_b128 v[12:15], v16 offset:3264
	s_waitcnt lgkmcnt(3)
	global_store_dwordx4 v169, v[0:3], s[100:101]
	s_add_u32 s100, s100, 0x4000
	s_addc_u32 s101, s101, 0
	s_waitcnt lgkmcnt(2)
	global_store_dwordx4 v169, v[4:7], s[100:101]
	s_add_u32 s100, s100, 0x4000
	s_addc_u32 s101, s101, 0
	s_waitcnt lgkmcnt(1)
	global_store_dwordx4 v169, v[8:11], s[100:101]
	s_add_u32 s100, s100, 0x4000
	s_addc_u32 s101, s101, 0
	s_waitcnt lgkmcnt(0)
	global_store_dwordx4 v169, v[12:15], s[100:101]
	s_add_u32 s100, s100, 0x4000
	s_addc_u32 s101, s101, 0
	ds_read_b128 v[0:3], v16 offset:4352
	ds_read_b128 v[4:7], v16 offset:5440
	ds_read_b128 v[8:11], v16 offset:6528
	ds_read_b128 v[12:15], v16 offset:7616
	s_waitcnt lgkmcnt(3)
	global_store_dwordx4 v169, v[0:3], s[100:101]
	s_add_u32 s100, s100, 0x4000
	s_addc_u32 s101, s101, 0
	s_waitcnt lgkmcnt(2)
	global_store_dwordx4 v169, v[4:7], s[100:101]
	s_add_u32 s100, s100, 0x4000
	s_addc_u32 s101, s101, 0
	s_waitcnt lgkmcnt(1)
	global_store_dwordx4 v169, v[8:11], s[100:101]
	s_add_u32 s100, s100, 0x4000
	s_addc_u32 s101, s101, 0
	s_waitcnt lgkmcnt(0)
	global_store_dwordx4 v169, v[12:15], s[100:101]
	s_add_u32 s100, s100, 0x4000
	s_addc_u32 s101, s101, 0
	s_branch .Lof3_d
.Lof3_h:
	v_lshrrev_b32_e32 v16, 6, v250
	v_mul_u32_u24_e32 v16, 0x1200, v16
	v_lshrrev_b32_e32 v17, 3, v225
	v_mul_u32_u24_e32 v17, 0x90, v17
	v_and_b32_e32 v18, 7, v225
	v_lshl_add_u32 v17, v18, 4, v17
	v_add_u32_e32 v16, v16, v17
	v_add_u32_e32 v16, 0x1000, v16
	ds_read_b128 v[0:3], v16
	ds_read_b128 v[4:7], v16 offset:1152
	ds_read_b128 v[8:11], v16 offset:2304
	ds_read_b128 v[12:15], v16 offset:3456
	s_waitcnt lgkmcnt(3)
	global_store_dwordx4 v169, v[0:3], s[100:101]
	s_add_u32 s100, s100, 0x4000
	s_addc_u32 s101, s101, 0
	s_waitcnt lgkmcnt(2)
	global_store_dwordx4 v169, v[4:7], s[100:101]
	s_add_u32 s100, s100, 0x4000
	s_addc_u32 s101, s101, 0
	s_waitcnt lgkmcnt(1)
	global_store_dwordx4 v169, v[8:11], s[100:101]
	s_add_u32 s100, s100, 0x4000
	s_addc_u32 s101, s101, 0
	s_waitcnt lgkmcnt(0)
	global_store_dwordx4 v169, v[12:15], s[100:101]
	s_add_u32 s100, s100, 0x4000
	s_addc_u32 s101, s101, 0
